# P6 scan2 hand-written batched loads + P8 epilogue 8-row x fetch + P0 transposes 4 loads in flight
# speedup vs baseline: 1.1120x; 1.0099x over previous
; DEV int ltid() { int t = threadIdx.x; asm volatile("" : "+v"(t)); return t; }
; DEV unsigned pack2(float a, float b) { float2v v = {a, b}; return __builtin_bit_cast(unsigned, __builtin_convertvector(v, bf16x2v)); }
; DEV void ph_transpose(const float* src, int K, int N, int Npad, u16* dst, int item, float* sm) {
;   const int ntl = Npad / 64, kt = item / ntl, nti = item % ntl, tid = ltid();
;   const int c4 = tid & 15, r0 = tid >> 4;
;   float4 v[4];
; #pragma unroll
;   for (int ps = 0; ps < 4; ++ps) {
;     const int k = ps * 16 + r0, n = nti * 64 + c4 * 4;
;     v[ps] = (n < N) ? *(const float4*)(src + (size_t)(kt * 64 + k) * N + n) : make_float4(0.f, 0.f, 0.f, 0.f);
;   }
; #pragma unroll
;   for (int ps = 0; ps < 4; ++ps) {
;     const int k = ps * 16 + r0;
;     sm[k * 65 + c4 * 4 + 0] = v[ps].x; sm[k * 65 + c4 * 4 + 1] = v[ps].y; sm[k * 65 + c4 * 4 + 2] = v[ps].z; sm[k * 65 + c4 * 4 + 3] = v[ps].w;
;   }
;   __syncthreads();
;   {
;     const int n = tid >> 2, q = tid & 3;
;     u32x4 o0, o1;
; #pragma unroll
;     for (int e = 0; e < 4; ++e) {
;       o0[e] = pack2(sm[(q * 16 + 2 * e) * 65 + n], sm[(q * 16 + 2 * e + 1) * 65 + n]);
;       o1[e] = pack2(sm[(q * 16 + 8 + 2 * e) * 65 + n], sm[(q * 16 + 8 + 2 * e + 1) * 65 + n]);
;     }
;     u16* d = dst + (size_t)(nti * 64 + n) * K + kt * 64 + q * 16;
;     *(u32x4*)d = o0; *(u32x4*)(d + 8) = o1;
;   }
;   __syncthreads();
; }
.LBB0_47:
	s_andn2_b64 vcc, exec, s[12:13]
	s_cbranch_vccnz .LBB0_49
	s_lshl_b32 s12, s9, 6
	v_mov_b32_e32 v8, v0
	s_and_b32 s13, s12, 64
	s_lshl_b32 s12, s9, 5
	s_waitcnt lgkmcnt(0)
	s_load_dwordx16 s[36:51], s[0:1], 0x40
	s_addk_i32 s12, 0x1800
	v_lshlrev_b32_e32 v2, 2, v8
	v_ashrrev_i32_e32 v9, 4, v8
	v_and_b32_e32 v10, 60, v2
	s_and_b32 s12, s12, 0x1fc0
	v_or_b32_e32 v3, s13, v10
	v_add_u32_e32 v2, s12, v9
	v_lshlrev_b32_e32 v36, 2, v3
	v_ashrrev_i32_e32 v3, 31, v2
	s_waitcnt lgkmcnt(0)
	v_lshl_add_u64 v[4:5], s[46:47], 0, v[36:37]
	v_lshlrev_b64 v[2:3], 9, v[2:3]
	v_lshl_add_u64 v[6:7], v[4:5], 0, v[2:3]
	v_lshl_add_u32 v2, v9, 6, v9
	v_add_lshl_u32 v9, v2, v10, 2
	global_load_dwordx4 v[2:5], v[6:7], off
	s_movk_i32 s14, 0x4000
	v_ashrrev_i32_e32 v12, 2, v8
	s_lshl_b32 s16, s12, 1
	v_add_co_u32_e32 v16, vcc, s35, v6
	s_nop 1
	v_addc_co_u32_e32 v17, vcc, 0, v7, vcc
	global_load_dwordx4 v[16:19], v[16:17], off
	v_add_co_u32_e32 v20, vcc, s14, v6
	s_nop 1
	v_addc_co_u32_e32 v21, vcc, 0, v7, vcc
	global_load_dwordx4 v[20:23], v[20:21], off
	v_add_co_u32_e32 v24, vcc, s93, v6
	s_nop 1
	v_addc_co_u32_e32 v25, vcc, 0, v7, vcc
	global_load_dwordx4 v[24:27], v[24:25], off
	s_waitcnt vmcnt(3)
	ds_write2_b32 v9, v2, v3 offset1:1
	ds_write2_b32 v9, v4, v5 offset0:2 offset1:3
	s_waitcnt vmcnt(2)
	v_add_u32_e32 v10, 0x1040, v9
	ds_write2_b32 v10, v16, v17 offset1:1
	v_add_u32_e32 v2, 0x1048, v9
	ds_write2_b32 v2, v18, v19 offset1:1
	s_waitcnt vmcnt(1)
	v_add_u32_e32 v10, 0x2080, v9
	ds_write2_b32 v10, v20, v21 offset1:1
	v_add_u32_e32 v2, 0x2088, v9
	ds_write2_b32 v2, v22, v23 offset1:1
	s_waitcnt vmcnt(0)
	v_add_u32_e32 v10, 0x30c0, v9
	ds_write2_b32 v10, v24, v25 offset1:1
	v_add_u32_e32 v2, 0x30c8, v9
	ds_write2_b32 v2, v26, v27 offset1:1
	v_lshlrev_b32_e32 v2, 4, v8
	v_and_b32_e32 v13, 48, v2
	v_mul_u32_u24_e32 v2, 0x41, v13
	v_and_b32_e32 v3, -4, v8
	v_lshl_add_u32 v8, v2, 2, v3
	v_add_u32_e32 v7, 0x800, v8
	s_waitcnt lgkmcnt(0)
	s_barrier
	ds_read2_b32 v[4:5], v7 offset0:8 offset1:73
	ds_read2_b32 v[2:3], v8 offset1:65
	v_add_u32_e32 v10, 0x400, v8
	v_add_u32_e32 v14, 0xc00, v8
	v_lshlrev_b32_e32 v36, 1, v13
	s_waitcnt lgkmcnt(1)
	v_cvt_pk_bf16_f32 v6, v4, v5
	ds_read2_b32 v[4:5], v8 offset0:130 offset1:195
	s_waitcnt lgkmcnt(1)
	v_cvt_pk_bf16_f32 v2, v2, v3
	ds_read2_b32 v[8:9], v14 offset0:12 offset1:77
	s_waitcnt lgkmcnt(1)
	v_cvt_pk_bf16_f32 v3, v4, v5
	ds_read2_b32 v[4:5], v7 offset0:138 offset1:203
	s_waitcnt lgkmcnt(1)
	v_cvt_pk_bf16_f32 v8, v8, v9
	s_waitcnt lgkmcnt(0)
	v_cvt_pk_bf16_f32 v7, v4, v5
	ds_read2_b32 v[4:5], v10 offset0:4 offset1:69
	ds_read2_b32 v[10:11], v10 offset0:134 offset1:199
	s_waitcnt lgkmcnt(1)
	v_cvt_pk_bf16_f32 v4, v4, v5
	s_waitcnt lgkmcnt(0)
	v_cvt_pk_bf16_f32 v5, v10, v11
	ds_read2_b32 v[10:11], v14 offset0:142 offset1:207
	s_waitcnt lgkmcnt(0)
	v_cvt_pk_bf16_f32 v9, v10, v11
	v_add_u32_e32 v10, s13, v12
	v_ashrrev_i32_e32 v11, 31, v10
	v_lshlrev_b64 v[10:11], 13, v[10:11]
	v_lshl_add_u64 v[10:11], s[54:55], 0, v[10:11]
	v_lshl_add_u64 v[10:11], v[10:11], 0, s[16:17]
	v_lshl_add_u64 v[10:11], v[10:11], 0, v[36:37]
	global_store_dwordx4 v[10:11], v[2:5], off
	global_store_dwordx4 v[10:11], v[6:9], off offset:16
	s_barrier

; DEV int ltid() { int t = threadIdx.x; asm volatile("" : "+v"(t)); return t; }
; DEV unsigned pack2(float a, float b) { float2v v = {a, b}; return __builtin_bit_cast(unsigned, __builtin_convertvector(v, bf16x2v)); }
; DEV void ph_transpose(const float* src, int K, int N, int Npad, u16* dst, int item, float* sm) {
;   const int ntl = Npad / 64, kt = item / ntl, nti = item % ntl, tid = ltid();
;   const int c4 = tid & 15, r0 = tid >> 4;
;   float4 v[4];
; #pragma unroll
;   for (int ps = 0; ps < 4; ++ps) {
;     const int k = ps * 16 + r0, n = nti * 64 + c4 * 4;
;     v[ps] = (n < N) ? *(const float4*)(src + (size_t)(kt * 64 + k) * N + n) : make_float4(0.f, 0.f, 0.f, 0.f);
;   }
; #pragma unroll
;   for (int ps = 0; ps < 4; ++ps) {
;     const int k = ps * 16 + r0;
;     sm[k * 65 + c4 * 4 + 0] = v[ps].x; sm[k * 65 + c4 * 4 + 1] = v[ps].y; sm[k * 65 + c4 * 4 + 2] = v[ps].z; sm[k * 65 + c4 * 4 + 3] = v[ps].w;
;   }
;   __syncthreads();
;   {
;     const int n = tid >> 2, q = tid & 3;
;     u32x4 o0, o1;
; #pragma unroll
;     for (int e = 0; e < 4; ++e) {
;       o0[e] = pack2(sm[(q * 16 + 2 * e) * 65 + n], sm[(q * 16 + 2 * e + 1) * 65 + n]);
;       o1[e] = pack2(sm[(q * 16 + 8 + 2 * e) * 65 + n], sm[(q * 16 + 8 + 2 * e + 1) * 65 + n]);
;     }
;     u16* d = dst + (size_t)(nti * 64 + n) * K + kt * 64 + q * 16;
;     *(u32x4*)d = o0; *(u32x4*)(d + 8) = o1;
;   }
;   __syncthreads();
; }
.LBB0_50:
	s_andn2_b64 vcc, exec, s[12:13]
	s_cbranch_vccnz .LBB0_52
	s_lshl_b32 s12, s9, 6
	v_mov_b32_e32 v8, v0
	s_and_b32 s13, s12, 64
	s_lshl_b32 s12, s9, 5
	s_waitcnt lgkmcnt(0)
	s_load_dwordx16 s[36:51], s[0:1], 0x40
	s_addk_i32 s12, 0x800
	v_lshlrev_b32_e32 v2, 2, v8
	v_ashrrev_i32_e32 v9, 4, v8
	v_and_b32_e32 v10, 60, v2
	s_and_b32 s12, s12, 0x1fc0
	v_or_b32_e32 v3, s13, v10
	v_add_u32_e32 v2, s12, v9
	v_lshlrev_b32_e32 v36, 2, v3
	v_ashrrev_i32_e32 v3, 31, v2
	s_waitcnt lgkmcnt(0)
	v_lshl_add_u64 v[4:5], s[44:45], 0, v[36:37]
	v_lshlrev_b64 v[2:3], 9, v[2:3]
	v_lshl_add_u64 v[6:7], v[4:5], 0, v[2:3]
	v_lshl_add_u32 v2, v9, 6, v9
	v_add_lshl_u32 v9, v2, v10, 2
	global_load_dwordx4 v[2:5], v[6:7], off
	s_movk_i32 s14, 0x4000
	v_ashrrev_i32_e32 v12, 2, v8
	s_lshl_b32 s16, s12, 1
	v_add_co_u32_e32 v16, vcc, s35, v6
	s_nop 1
	v_addc_co_u32_e32 v17, vcc, 0, v7, vcc
	global_load_dwordx4 v[16:19], v[16:17], off
	v_add_co_u32_e32 v20, vcc, s14, v6
	s_nop 1
	v_addc_co_u32_e32 v21, vcc, 0, v7, vcc
	global_load_dwordx4 v[20:23], v[20:21], off
	v_add_co_u32_e32 v24, vcc, s93, v6
	s_nop 1
	v_addc_co_u32_e32 v25, vcc, 0, v7, vcc
	global_load_dwordx4 v[24:27], v[24:25], off
	s_waitcnt vmcnt(3)
	ds_write2_b32 v9, v2, v3 offset1:1
	ds_write2_b32 v9, v4, v5 offset0:2 offset1:3
	s_waitcnt vmcnt(2)
	v_add_u32_e32 v10, 0x1040, v9
	ds_write2_b32 v10, v16, v17 offset1:1
	v_add_u32_e32 v2, 0x1048, v9
	ds_write2_b32 v2, v18, v19 offset1:1
	s_waitcnt vmcnt(1)
	v_add_u32_e32 v10, 0x2080, v9
	ds_write2_b32 v10, v20, v21 offset1:1
	v_add_u32_e32 v2, 0x2088, v9
	ds_write2_b32 v2, v22, v23 offset1:1
	s_waitcnt vmcnt(0)
	v_add_u32_e32 v10, 0x30c0, v9
	ds_write2_b32 v10, v24, v25 offset1:1
	v_add_u32_e32 v2, 0x30c8, v9
	ds_write2_b32 v2, v26, v27 offset1:1
	v_lshlrev_b32_e32 v2, 4, v8
	v_and_b32_e32 v13, 48, v2
	v_mul_u32_u24_e32 v2, 0x41, v13
	v_and_b32_e32 v3, -4, v8
	v_lshl_add_u32 v8, v2, 2, v3
	v_add_u32_e32 v7, 0x800, v8
	s_waitcnt lgkmcnt(0)
	s_barrier
	ds_read2_b32 v[4:5], v7 offset0:8 offset1:73
	ds_read2_b32 v[2:3], v8 offset1:65
	v_add_u32_e32 v10, 0x400, v8
	v_add_u32_e32 v14, 0xc00, v8
	v_lshlrev_b32_e32 v36, 1, v13
	s_waitcnt lgkmcnt(1)
	v_cvt_pk_bf16_f32 v6, v4, v5
	ds_read2_b32 v[4:5], v8 offset0:130 offset1:195
	s_waitcnt lgkmcnt(1)
	v_cvt_pk_bf16_f32 v2, v2, v3
	ds_read2_b32 v[8:9], v14 offset0:12 offset1:77
	s_waitcnt lgkmcnt(1)
	v_cvt_pk_bf16_f32 v3, v4, v5
	ds_read2_b32 v[4:5], v7 offset0:138 offset1:203
	s_waitcnt lgkmcnt(1)
	v_cvt_pk_bf16_f32 v8, v8, v9
	s_waitcnt lgkmcnt(0)
	v_cvt_pk_bf16_f32 v7, v4, v5
	ds_read2_b32 v[4:5], v10 offset0:4 offset1:69
	ds_read2_b32 v[10:11], v10 offset0:134 offset1:199
	s_waitcnt lgkmcnt(1)
	v_cvt_pk_bf16_f32 v4, v4, v5
	s_waitcnt lgkmcnt(0)
	v_cvt_pk_bf16_f32 v5, v10, v11
	ds_read2_b32 v[10:11], v14 offset0:142 offset1:207
	s_waitcnt lgkmcnt(0)
	v_cvt_pk_bf16_f32 v9, v10, v11
	v_add_u32_e32 v10, s13, v12
	v_ashrrev_i32_e32 v11, 31, v10
	v_lshlrev_b64 v[10:11], 13, v[10:11]
	v_lshl_add_u64 v[10:11], s[52:53], 0, v[10:11]
	v_lshl_add_u64 v[10:11], v[10:11], 0, s[16:17]
	v_lshl_add_u64 v[10:11], v[10:11], 0, v[36:37]
	global_store_dwordx4 v[10:11], v[2:5], off
	global_store_dwordx4 v[10:11], v[6:9], off offset:16
	s_barrier

; DEV int ltid() { int t = threadIdx.x; asm volatile("" : "+v"(t)); return t; }
; DEV unsigned pack2(float a, float b) { float2v v = {a, b}; return __builtin_bit_cast(unsigned, __builtin_convertvector(v, bf16x2v)); }
; DEV void ph_transpose(const float* src, int K, int N, int Npad, u16* dst, int item, float* sm) {
;   const int ntl = Npad / 64, kt = item / ntl, nti = item % ntl, tid = ltid();
;   const int c4 = tid & 15, r0 = tid >> 4;
;   float4 v[4];
; #pragma unroll
;   for (int ps = 0; ps < 4; ++ps) {
;     const int k = ps * 16 + r0, n = nti * 64 + c4 * 4;
;     v[ps] = (n < N) ? *(const float4*)(src + (size_t)(kt * 64 + k) * N + n) : make_float4(0.f, 0.f, 0.f, 0.f);
;   }
; #pragma unroll
;   for (int ps = 0; ps < 4; ++ps) {
;     const int k = ps * 16 + r0;
;     sm[k * 65 + c4 * 4 + 0] = v[ps].x; sm[k * 65 + c4 * 4 + 1] = v[ps].y; sm[k * 65 + c4 * 4 + 2] = v[ps].z; sm[k * 65 + c4 * 4 + 3] = v[ps].w;
;   }
;   __syncthreads();
;   {
;     const int n = tid >> 2, q = tid & 3;
;     u32x4 o0, o1;
; #pragma unroll
;     for (int e = 0; e < 4; ++e) {
;       o0[e] = pack2(sm[(q * 16 + 2 * e) * 65 + n], sm[(q * 16 + 2 * e + 1) * 65 + n]);
;       o1[e] = pack2(sm[(q * 16 + 8 + 2 * e) * 65 + n], sm[(q * 16 + 8 + 2 * e + 1) * 65 + n]);
;     }
;     u16* d = dst + (size_t)(nti * 64 + n) * K + kt * 64 + q * 16;
;     *(u32x4*)d = o0; *(u32x4*)(d + 8) = o1;
;   }
;   __syncthreads();
; }
.LBB0_53:
	s_andn2_b64 vcc, exec, s[12:13]
	s_cbranch_vccnz .LBB0_55
	s_lshl_b32 s12, s9, 6
	v_mov_b32_e32 v8, v0
	s_and_b32 s13, s12, 0x7c0
	s_lshl_b32 s12, s9, 1
	s_waitcnt lgkmcnt(0)
	s_load_dwordx16 s[36:51], s[0:1], 0xc0
	s_add_i32 s12, s12, 0x1e280
	v_lshlrev_b32_e32 v2, 2, v8
	v_ashrrev_i32_e32 v9, 4, v8
	v_and_b32_e32 v10, 60, v2
	s_and_b32 s12, s12, 0x1ffc0
	v_or_b32_e32 v3, s13, v10
	v_add_u32_e32 v2, s12, v9
	v_lshlrev_b32_e32 v36, 2, v3
	v_ashrrev_i32_e32 v3, 31, v2
	s_waitcnt lgkmcnt(0)
	v_lshl_add_u64 v[4:5], s[36:37], 0, v[36:37]
	v_lshlrev_b64 v[2:3], 13, v[2:3]
	v_lshl_add_u64 v[6:7], v[4:5], 0, v[2:3]
	v_lshl_add_u32 v2, v9, 6, v9
	v_add_lshl_u32 v9, v2, v10, 2
	global_load_dwordx4 v[2:5], v[6:7], off
	v_ashrrev_i32_e32 v12, 2, v8
	s_lshl_b32 s16, s12, 1
	v_add_co_u32_e32 v16, vcc, s96, v6
	s_nop 1
	v_addc_co_u32_e32 v17, vcc, 0, v7, vcc
	global_load_dwordx4 v[16:19], v[16:17], off
	v_add_co_u32_e32 v20, vcc, s97, v6
	s_nop 1
	v_addc_co_u32_e32 v21, vcc, 0, v7, vcc
	global_load_dwordx4 v[20:23], v[20:21], off
	v_add_co_u32_e32 v24, vcc, s5, v6
	s_nop 1
	v_addc_co_u32_e32 v25, vcc, 0, v7, vcc
	global_load_dwordx4 v[24:27], v[24:25], off
	s_waitcnt vmcnt(3)
	ds_write2_b32 v9, v2, v3 offset1:1
	ds_write2_b32 v9, v4, v5 offset0:2 offset1:3
	s_waitcnt vmcnt(2)
	v_add_u32_e32 v10, 0x1040, v9
	ds_write2_b32 v10, v16, v17 offset1:1
	v_add_u32_e32 v2, 0x1048, v9
	ds_write2_b32 v2, v18, v19 offset1:1
	s_waitcnt vmcnt(1)
	v_add_u32_e32 v10, 0x2080, v9
	ds_write2_b32 v10, v20, v21 offset1:1
	v_add_u32_e32 v2, 0x2088, v9
	ds_write2_b32 v2, v22, v23 offset1:1
	s_waitcnt vmcnt(0)
	v_add_u32_e32 v10, 0x30c0, v9
	ds_write2_b32 v10, v24, v25 offset1:1
	v_add_u32_e32 v2, 0x30c8, v9
	ds_write2_b32 v2, v26, v27 offset1:1
	v_lshlrev_b32_e32 v2, 4, v8
	v_and_b32_e32 v13, 48, v2
	v_mul_u32_u24_e32 v2, 0x41, v13
	v_and_b32_e32 v3, -4, v8
	v_lshl_add_u32 v8, v2, 2, v3
	v_add_u32_e32 v7, 0x800, v8
	s_waitcnt lgkmcnt(0)
	s_barrier
	ds_read2_b32 v[4:5], v7 offset0:8 offset1:73
	ds_read2_b32 v[2:3], v8 offset1:65
	v_add_u32_e32 v10, 0x400, v8
	v_add_u32_e32 v14, 0xc00, v8
	v_lshlrev_b32_e32 v36, 1, v13
	s_waitcnt lgkmcnt(1)
	v_cvt_pk_bf16_f32 v6, v4, v5
	ds_read2_b32 v[4:5], v8 offset0:130 offset1:195
	s_waitcnt lgkmcnt(1)
	v_cvt_pk_bf16_f32 v2, v2, v3
	ds_read2_b32 v[8:9], v14 offset0:12 offset1:77
	s_waitcnt lgkmcnt(1)
	v_cvt_pk_bf16_f32 v3, v4, v5
	ds_read2_b32 v[4:5], v7 offset0:138 offset1:203
	s_waitcnt lgkmcnt(1)
	v_cvt_pk_bf16_f32 v8, v8, v9
	s_waitcnt lgkmcnt(0)
	v_cvt_pk_bf16_f32 v7, v4, v5
	ds_read2_b32 v[4:5], v10 offset0:4 offset1:69
	ds_read2_b32 v[10:11], v10 offset0:134 offset1:199
	s_waitcnt lgkmcnt(1)
	v_cvt_pk_bf16_f32 v4, v4, v5
	s_waitcnt lgkmcnt(0)
	v_cvt_pk_bf16_f32 v5, v10, v11
	ds_read2_b32 v[10:11], v14 offset0:142 offset1:207
	s_waitcnt lgkmcnt(0)
	v_cvt_pk_bf16_f32 v9, v10, v11
	v_add_u32_e32 v10, s13, v12
	v_ashrrev_i32_e32 v11, 31, v10
	v_lshlrev_b64 v[10:11], 6, v[10:11]
	v_lshl_add_u64 v[10:11], s[50:51], 0, v[10:11]
	v_lshrrev_b32_e32 v14, 6, v36
	v_lshrrev_b32_e64 v12, 6, s16
	v_add_u32_e32 v14, v14, v12
	v_mul_u32_u24_e32 v14, 0x20000, v14
	v_and_b32_e32 v36, 32, v36
	v_add_u32_e32 v36, v36, v14
	v_lshl_add_u64 v[10:11], v[10:11], 0, v[36:37]
	global_store_dwordx4 v[10:11], v[2:5], off
	global_store_dwordx4 v[10:11], v[6:9], off offset:16
	s_barrier

; DEV int ltid() { int t = threadIdx.x; asm volatile("" : "+v"(t)); return t; }
; DEV unsigned pack2(float a, float b) { float2v v = {a, b}; return __builtin_bit_cast(unsigned, __builtin_convertvector(v, bf16x2v)); }
; DEV void ph_transpose(const float* src, int K, int N, int Npad, u16* dst, int item, float* sm) {
;   const int ntl = Npad / 64, kt = item / ntl, nti = item % ntl, tid = ltid();
;   const int c4 = tid & 15, r0 = tid >> 4;
;   float4 v[4];
; #pragma unroll
;   for (int ps = 0; ps < 4; ++ps) {
;     const int k = ps * 16 + r0, n = nti * 64 + c4 * 4;
;     v[ps] = (n < N) ? *(const float4*)(src + (size_t)(kt * 64 + k) * N + n) : make_float4(0.f, 0.f, 0.f, 0.f);
;   }
; #pragma unroll
;   for (int ps = 0; ps < 4; ++ps) {
;     const int k = ps * 16 + r0;
;     sm[k * 65 + c4 * 4 + 0] = v[ps].x; sm[k * 65 + c4 * 4 + 1] = v[ps].y; sm[k * 65 + c4 * 4 + 2] = v[ps].z; sm[k * 65 + c4 * 4 + 3] = v[ps].w;
;   }
;   __syncthreads();
;   {
;     const int n = tid >> 2, q = tid & 3;
;     u32x4 o0, o1;
; #pragma unroll
;     for (int e = 0; e < 4; ++e) {
;       o0[e] = pack2(sm[(q * 16 + 2 * e) * 65 + n], sm[(q * 16 + 2 * e + 1) * 65 + n]);
;       o1[e] = pack2(sm[(q * 16 + 8 + 2 * e) * 65 + n], sm[(q * 16 + 8 + 2 * e + 1) * 65 + n]);
;     }
;     u16* d = dst + (size_t)(nti * 64 + n) * K + kt * 64 + q * 16;
;     *(u32x4*)d = o0; *(u32x4*)(d + 8) = o1;
;   }
;   __syncthreads();
; }
.LBB0_56:
	s_andn2_b64 vcc, exec, s[12:13]
	s_cbranch_vccnz .LBB0_58
	s_lshl_b32 s12, s9, 6
	v_mov_b32_e32 v8, v0
	s_and_b32 s13, s12, 0x7c0
	s_lshl_b32 s12, s9, 1
	s_waitcnt lgkmcnt(0)
	s_load_dwordx16 s[36:51], s[0:1], 0x0
	s_add_i32 s12, s12, 0x1ea80
	v_lshlrev_b32_e32 v2, 2, v8
	v_ashrrev_i32_e32 v9, 4, v8
	v_and_b32_e32 v10, 60, v2
	s_and_b32 s12, s12, 0x1ffc0
	v_or_b32_e32 v3, s13, v10
	v_add_u32_e32 v2, s12, v9
	v_lshlrev_b32_e32 v36, 2, v3
	v_ashrrev_i32_e32 v3, 31, v2
	s_waitcnt lgkmcnt(0)
	v_lshl_add_u64 v[4:5], s[50:51], 0, v[36:37]
	v_lshlrev_b64 v[2:3], 13, v[2:3]
	v_lshl_add_u64 v[6:7], v[4:5], 0, v[2:3]
	v_lshl_add_u32 v2, v9, 6, v9
	v_add_lshl_u32 v9, v2, v10, 2
	global_load_dwordx4 v[2:5], v[6:7], off
	v_ashrrev_i32_e32 v12, 2, v8
	s_load_dwordx16 s[36:51], s[0:1], 0xc0
	s_lshl_b32 s16, s12, 1
	v_add_co_u32_e32 v16, vcc, s96, v6
	s_nop 1
	v_addc_co_u32_e32 v17, vcc, 0, v7, vcc
	global_load_dwordx4 v[16:19], v[16:17], off
	v_add_co_u32_e32 v20, vcc, s97, v6
	s_nop 1
	v_addc_co_u32_e32 v21, vcc, 0, v7, vcc
	global_load_dwordx4 v[20:23], v[20:21], off
	v_add_co_u32_e32 v24, vcc, s5, v6
	s_nop 1
	v_addc_co_u32_e32 v25, vcc, 0, v7, vcc
	global_load_dwordx4 v[24:27], v[24:25], off
	s_waitcnt vmcnt(3)
	ds_write2_b32 v9, v2, v3 offset1:1
	ds_write2_b32 v9, v4, v5 offset0:2 offset1:3
	s_waitcnt vmcnt(2)
	v_add_u32_e32 v10, 0x1040, v9
	ds_write2_b32 v10, v16, v17 offset1:1
	v_add_u32_e32 v2, 0x1048, v9
	ds_write2_b32 v2, v18, v19 offset1:1
	s_waitcnt vmcnt(1)
	v_add_u32_e32 v10, 0x2080, v9
	ds_write2_b32 v10, v20, v21 offset1:1
	v_add_u32_e32 v2, 0x2088, v9
	ds_write2_b32 v2, v22, v23 offset1:1
	s_waitcnt vmcnt(0)
	v_add_u32_e32 v10, 0x30c0, v9
	ds_write2_b32 v10, v24, v25 offset1:1
	v_add_u32_e32 v2, 0x30c8, v9
	ds_write2_b32 v2, v26, v27 offset1:1
	v_lshlrev_b32_e32 v2, 4, v8
	v_and_b32_e32 v13, 48, v2
	v_mul_u32_u24_e32 v2, 0x41, v13
	v_and_b32_e32 v3, -4, v8
	v_lshl_add_u32 v8, v2, 2, v3
	v_add_u32_e32 v7, 0x800, v8
	s_waitcnt lgkmcnt(0)
	s_barrier
	ds_read2_b32 v[4:5], v7 offset0:8 offset1:73
	ds_read2_b32 v[2:3], v8 offset1:65
	v_add_u32_e32 v10, 0x400, v8
	v_add_u32_e32 v14, 0xc00, v8
	v_lshlrev_b32_e32 v36, 1, v13
	s_waitcnt lgkmcnt(1)
	v_cvt_pk_bf16_f32 v6, v4, v5
	ds_read2_b32 v[4:5], v8 offset0:130 offset1:195
	s_waitcnt lgkmcnt(1)
	v_cvt_pk_bf16_f32 v2, v2, v3
	ds_read2_b32 v[8:9], v14 offset0:12 offset1:77
	s_waitcnt lgkmcnt(1)
	v_cvt_pk_bf16_f32 v3, v4, v5
	ds_read2_b32 v[4:5], v7 offset0:138 offset1:203
	s_waitcnt lgkmcnt(1)
	v_cvt_pk_bf16_f32 v8, v8, v9
	s_waitcnt lgkmcnt(0)
	v_cvt_pk_bf16_f32 v7, v4, v5
	ds_read2_b32 v[4:5], v10 offset0:4 offset1:69
	ds_read2_b32 v[10:11], v10 offset0:134 offset1:199
	s_waitcnt lgkmcnt(1)
	v_cvt_pk_bf16_f32 v4, v4, v5
	s_waitcnt lgkmcnt(0)
	v_cvt_pk_bf16_f32 v5, v10, v11
	ds_read2_b32 v[10:11], v14 offset0:142 offset1:207
	s_waitcnt lgkmcnt(0)
	v_cvt_pk_bf16_f32 v9, v10, v11
	v_add_u32_e32 v10, s13, v12
	v_ashrrev_i32_e32 v11, 31, v10
	v_lshlrev_b64 v[10:11], 6, v[10:11]
	v_lshl_add_u64 v[10:11], s[48:49], 0, v[10:11]
	v_lshrrev_b32_e32 v14, 6, v36
	v_lshrrev_b32_e64 v12, 6, s16
	v_add_u32_e32 v14, v14, v12
	v_mul_u32_u24_e32 v14, 0x20000, v14
	v_and_b32_e32 v36, 32, v36
	v_add_u32_e32 v36, v36, v14
	v_lshl_add_u64 v[10:11], v[10:11], 0, v[36:37]
	global_store_dwordx4 v[10:11], v[2:5], off
	global_store_dwordx4 v[10:11], v[6:9], off offset:16
	s_barrier

; __global__ void __launch_bounds__(256, 2) fwd_megakernel(Params p) {
;     ...
;   for (int e = bid * 256 + tid; e < 8 * 12288; e += nb * 256) {
;     int b = e / 12288, n = e % 12288;
;     float s = p.ada_b[n];
;     for (int kc = 0; kc < 32; ++kc) s += p.modpart[((size_t)(kc * 8 + b)) * 12288 + n];
;     p.mod[e] = s;
;   }
.LBB0_134:
	s_mov_b32 s3, 0x2aaaaaab
	v_mul_hi_i32 v1, v2, s3
	v_lshrrev_b32_e32 v3, 31, v1
	v_ashrrev_i32_e32 v1, 11, v1
	v_add_u32_e32 v3, v1, v3
	v_mul_i32_i24_e32 v1, 0x3000, v3
	v_sub_u32_e32 v4, v2, v1
	v_ashrrev_i32_e32 v5, 31, v4
	v_readlane_b32 s8, v254, 25
	v_lshlrev_b64 v[4:5], 2, v[4:5]
	v_readlane_b32 s14, v254, 31
	v_readlane_b32 s15, v254, 32
	s_mov_b32 s3, 0xc000
	v_readlane_b32 s9, v254, 26
	v_lshl_add_u64 v[6:7], s[14:15], 0, v[4:5]
	global_load_dword v1, v[6:7], off
	v_mad_i64_i32 v[4:5], s[4:5], v3, s3, v[4:5]
	v_lshl_add_u64 v[4:5], s[76:77], 0, v[4:5]
	s_mov_b64 s[8:9], 0
	v_readlane_b32 s10, v254, 27
	v_readlane_b32 s11, v254, 28
	v_readlane_b32 s12, v254, 29
	v_readlane_b32 s13, v254, 30
	v_readlane_b32 s16, v254, 33
	v_readlane_b32 s17, v254, 34
	v_readlane_b32 s18, v254, 35
	v_readlane_b32 s19, v254, 36
	v_readlane_b32 s20, v254, 37
	v_readlane_b32 s21, v254, 38
	v_readlane_b32 s22, v254, 39
	v_readlane_b32 s23, v254, 40
	v_lshl_add_u64 v[6:7], v[4:5], 0, s[8:9]
	global_load_dword v10, v[6:7], off
	s_add_u32 s8, s8, 0x60000
	s_addc_u32 s9, s9, 0
	v_lshl_add_u64 v[6:7], v[4:5], 0, s[8:9]
	global_load_dword v11, v[6:7], off
	s_add_u32 s8, s8, 0x60000
	s_addc_u32 s9, s9, 0
	v_lshl_add_u64 v[6:7], v[4:5], 0, s[8:9]
	global_load_dword v12, v[6:7], off
	s_add_u32 s8, s8, 0x60000
	s_addc_u32 s9, s9, 0
	v_lshl_add_u64 v[6:7], v[4:5], 0, s[8:9]
	global_load_dword v13, v[6:7], off
	s_add_u32 s8, s8, 0x60000
	s_addc_u32 s9, s9, 0
	v_lshl_add_u64 v[6:7], v[4:5], 0, s[8:9]
	global_load_dword v14, v[6:7], off
	s_add_u32 s8, s8, 0x60000
	s_addc_u32 s9, s9, 0
	v_lshl_add_u64 v[6:7], v[4:5], 0, s[8:9]
	global_load_dword v15, v[6:7], off
	s_add_u32 s8, s8, 0x60000
	s_addc_u32 s9, s9, 0
	v_lshl_add_u64 v[6:7], v[4:5], 0, s[8:9]
	global_load_dword v16, v[6:7], off
	s_add_u32 s8, s8, 0x60000
	s_addc_u32 s9, s9, 0
	v_lshl_add_u64 v[6:7], v[4:5], 0, s[8:9]
	global_load_dword v17, v[6:7], off
	s_add_u32 s8, s8, 0x60000
	s_addc_u32 s9, s9, 0
	v_lshl_add_u64 v[6:7], v[4:5], 0, s[8:9]
	global_load_dword v18, v[6:7], off
	s_add_u32 s8, s8, 0x60000
	s_addc_u32 s9, s9, 0
	v_lshl_add_u64 v[6:7], v[4:5], 0, s[8:9]
	global_load_dword v19, v[6:7], off
	s_add_u32 s8, s8, 0x60000
	s_addc_u32 s9, s9, 0
	v_lshl_add_u64 v[6:7], v[4:5], 0, s[8:9]
	global_load_dword v20, v[6:7], off
	s_add_u32 s8, s8, 0x60000
	s_addc_u32 s9, s9, 0
	v_lshl_add_u64 v[6:7], v[4:5], 0, s[8:9]
	global_load_dword v21, v[6:7], off
	s_add_u32 s8, s8, 0x60000
	s_addc_u32 s9, s9, 0
	v_lshl_add_u64 v[6:7], v[4:5], 0, s[8:9]
	global_load_dword v22, v[6:7], off
	s_add_u32 s8, s8, 0x60000
	s_addc_u32 s9, s9, 0
	v_lshl_add_u64 v[6:7], v[4:5], 0, s[8:9]
	global_load_dword v23, v[6:7], off
	s_add_u32 s8, s8, 0x60000
	s_addc_u32 s9, s9, 0
	v_lshl_add_u64 v[6:7], v[4:5], 0, s[8:9]
	global_load_dword v24, v[6:7], off
	s_add_u32 s8, s8, 0x60000
	s_addc_u32 s9, s9, 0
	v_lshl_add_u64 v[6:7], v[4:5], 0, s[8:9]
	global_load_dword v25, v[6:7], off
	s_add_u32 s8, s8, 0x60000
	s_addc_u32 s9, s9, 0
	v_lshl_add_u64 v[6:7], v[4:5], 0, s[8:9]
	global_load_dword v26, v[6:7], off
	s_add_u32 s8, s8, 0x60000
	s_addc_u32 s9, s9, 0
	v_lshl_add_u64 v[6:7], v[4:5], 0, s[8:9]
	global_load_dword v27, v[6:7], off
	s_add_u32 s8, s8, 0x60000
	s_addc_u32 s9, s9, 0
	v_lshl_add_u64 v[6:7], v[4:5], 0, s[8:9]
	global_load_dword v28, v[6:7], off
	s_add_u32 s8, s8, 0x60000
	s_addc_u32 s9, s9, 0
	v_lshl_add_u64 v[6:7], v[4:5], 0, s[8:9]
	global_load_dword v29, v[6:7], off
	s_add_u32 s8, s8, 0x60000
	s_addc_u32 s9, s9, 0
	v_lshl_add_u64 v[6:7], v[4:5], 0, s[8:9]
	global_load_dword v30, v[6:7], off
	s_add_u32 s8, s8, 0x60000
	s_addc_u32 s9, s9, 0
	v_lshl_add_u64 v[6:7], v[4:5], 0, s[8:9]
	global_load_dword v31, v[6:7], off
	s_add_u32 s8, s8, 0x60000
	s_addc_u32 s9, s9, 0
	v_lshl_add_u64 v[6:7], v[4:5], 0, s[8:9]
	global_load_dword v32, v[6:7], off
	s_add_u32 s8, s8, 0x60000
	s_addc_u32 s9, s9, 0
	v_lshl_add_u64 v[6:7], v[4:5], 0, s[8:9]
	global_load_dword v33, v[6:7], off
	s_add_u32 s8, s8, 0x60000
	s_addc_u32 s9, s9, 0
	v_lshl_add_u64 v[6:7], v[4:5], 0, s[8:9]
	global_load_dword v34, v[6:7], off
	s_add_u32 s8, s8, 0x60000
	s_addc_u32 s9, s9, 0
	v_lshl_add_u64 v[6:7], v[4:5], 0, s[8:9]
	global_load_dword v35, v[6:7], off
	s_add_u32 s8, s8, 0x60000
	s_addc_u32 s9, s9, 0
	v_lshl_add_u64 v[6:7], v[4:5], 0, s[8:9]
	global_load_dword v36, v[6:7], off
	s_add_u32 s8, s8, 0x60000
	s_addc_u32 s9, s9, 0
	v_lshl_add_u64 v[6:7], v[4:5], 0, s[8:9]
	global_load_dword v37, v[6:7], off
	s_add_u32 s8, s8, 0x60000
	s_addc_u32 s9, s9, 0
	v_lshl_add_u64 v[6:7], v[4:5], 0, s[8:9]
	global_load_dword v38, v[6:7], off
	s_add_u32 s8, s8, 0x60000
	s_addc_u32 s9, s9, 0
	v_lshl_add_u64 v[6:7], v[4:5], 0, s[8:9]
	global_load_dword v39, v[6:7], off
	s_add_u32 s8, s8, 0x60000
	s_addc_u32 s9, s9, 0
	v_lshl_add_u64 v[6:7], v[4:5], 0, s[8:9]
	global_load_dword v40, v[6:7], off
	s_add_u32 s8, s8, 0x60000
	s_addc_u32 s9, s9, 0
	v_lshl_add_u64 v[6:7], v[4:5], 0, s[8:9]
	global_load_dword v41, v[6:7], off
	s_add_u32 s8, s8, 0x60000
	s_addc_u32 s9, s9, 0
	s_waitcnt vmcnt(0)
	v_add_f32_e32 v1, v1, v10
	v_add_f32_e32 v1, v1, v11
	v_add_f32_e32 v1, v1, v12
	v_add_f32_e32 v1, v1, v13
	v_add_f32_e32 v1, v1, v14
	v_add_f32_e32 v1, v1, v15
	v_add_f32_e32 v1, v1, v16
	v_add_f32_e32 v1, v1, v17
	v_add_f32_e32 v1, v1, v18
	v_add_f32_e32 v1, v1, v19
	v_add_f32_e32 v1, v1, v20
	v_add_f32_e32 v1, v1, v21
	v_add_f32_e32 v1, v1, v22
	v_add_f32_e32 v1, v1, v23
	v_add_f32_e32 v1, v1, v24
	v_add_f32_e32 v1, v1, v25
	v_add_f32_e32 v1, v1, v26
	v_add_f32_e32 v1, v1, v27
	v_add_f32_e32 v1, v1, v28
	v_add_f32_e32 v1, v1, v29
	v_add_f32_e32 v1, v1, v30
	v_add_f32_e32 v1, v1, v31
	v_add_f32_e32 v1, v1, v32
	v_add_f32_e32 v1, v1, v33
	v_add_f32_e32 v1, v1, v34
	v_add_f32_e32 v1, v1, v35
	v_add_f32_e32 v1, v1, v36
	v_add_f32_e32 v1, v1, v37
	v_add_f32_e32 v1, v1, v38
	v_add_f32_e32 v1, v1, v39
	v_add_f32_e32 v1, v1, v40
	v_add_f32_e32 v1, v1, v41
	v_ashrrev_i32_e32 v3, 31, v2
	v_lshl_add_u64 v[4:5], v[2:3], 2, s[78:79]
	v_add_u32_e32 v2, s2, v2
	s_mov_b32 s3, 0x17fff
	v_cmp_lt_i32_e32 vcc, s3, v2
	s_or_b64 s[6:7], vcc, s[6:7]
	global_store_dword v[4:5], v1, off
	s_andn2_b64 exec, exec, s[6:7]
	s_cbranch_execnz .LBB0_134

; DEV int ltid() { int t = threadIdx.x; asm volatile("" : "+v"(t)); return t; }
; DEV void ph_scan2(const Params& p, int item) {
;   const int b = item / NCH, c = item % NCH, ch = ltid() * 4;
;   float H[4] = {0.f, 0.f, 0.f, 0.f};
;   for (int c2 = 0; c2 < c; ++c2) {
;     float4 a = *(const float4*)(p.csA + (size_t)(b * NCH + c2) * 1024 + ch);
;     float4 hh = *(const float4*)(p.csH + (size_t)(b * NCH + c2) * 1024 + ch);
;     H[0] = a.x * H[0] + hh.x; H[1] = a.y * H[1] + hh.y; H[2] = a.z * H[2] + hh.z; H[3] = a.w * H[3] + hh.w;
;   }
;   const size_t row0 = (size_t)(b * S_ + c * CHL);
.LBB0_994:
	s_or_b64 exec, exec, s[0:1]
	v_mov_b32_e32 v1, v0
	s_cmpk_gt_i32 s94, 0x1ff
	s_waitcnt lgkmcnt(0)
	s_barrier
	s_cbranch_scc1 .LBB0_1132
	s_mov_b64 exec, -1
	v_lshlrev_b32_e32 v1, 4, v0
	v_lshlrev_b32_e32 v2, 3, v0
	v_mov_b32_e32 v8, 0x3ba10414
	v_mov_b32_e32 v9, 0xb9c68948
	v_mov_b32_e32 v3, 0x7f800000
	s_mov_b32 s72, 0x378e98ab
	s_mov_b32 s73, 0x3b7cd369
	s_mov_b32 s74, 0xbcc618b2
	s_mov_b32 s75, 0x3dda74e4
	s_mov_b32 s76, 0x3f228afd
	s_mov_b32 s77, 0x3e03c728
	s_mov_b32 s78, 0xbfb8aa3b
	s_mov_b32 s79, 0x42ce8ed0
	s_mov_b32 s80, 0xc2b17218
	s_brev_b32 s81, -2
	s_mov_b32 s50, s94
.Lsc_item:
	s_lshr_b32 s48, s50, 6
	s_and_b32 s49, s50, 63
	v_mov_b32_e32 v4, 0
	v_mov_b32_e32 v5, 0
	v_mov_b32_e32 v6, 0
	v_mov_b32_e32 v7, 0
	v_readlane_b32 s24, v255, 33
	v_readlane_b32 s25, v255, 34
	v_readlane_b32 s26, v255, 35
	v_readlane_b32 s27, v255, 36
	s_lshl_b32 s38, s48, 18
	s_add_u32 s24, s24, s38
	s_addc_u32 s25, s25, 0
	s_add_u32 s26, s26, s38
	s_addc_u32 s27, s27, 0
	s_mov_b32 s45, 0
.Lsc_pre:
	s_cmp_lt_u32 s45, s49
	s_cbranch_scc0 .Lsc_predone
	s_add_u32 s38, s45, 0
	s_cmp_lt_u32 s38, s49
	s_cbranch_scc0 .Lsc_pl0
	global_load_dwordx4 v[10:13], v1, s[24:25]
	global_load_dwordx4 v[14:17], v1, s[26:27]
	s_add_u32 s24, s24, 0x1000
	s_addc_u32 s25, s25, 0
	s_add_u32 s26, s26, 0x1000
	s_addc_u32 s27, s27, 0
.Lsc_pl0:
	s_add_u32 s38, s45, 1
	s_cmp_lt_u32 s38, s49
	s_cbranch_scc0 .Lsc_pl1
	global_load_dwordx4 v[18:21], v1, s[24:25]
	global_load_dwordx4 v[22:25], v1, s[26:27]
	s_add_u32 s24, s24, 0x1000
	s_addc_u32 s25, s25, 0
	s_add_u32 s26, s26, 0x1000
	s_addc_u32 s27, s27, 0
.Lsc_pl1:
	s_add_u32 s38, s45, 2
	s_cmp_lt_u32 s38, s49
	s_cbranch_scc0 .Lsc_pl2
	global_load_dwordx4 v[26:29], v1, s[24:25]
	global_load_dwordx4 v[30:33], v1, s[26:27]
	s_add_u32 s24, s24, 0x1000
	s_addc_u32 s25, s25, 0
	s_add_u32 s26, s26, 0x1000
	s_addc_u32 s27, s27, 0
.Lsc_pl2:
	s_add_u32 s38, s45, 3
	s_cmp_lt_u32 s38, s49
	s_cbranch_scc0 .Lsc_pl3
	global_load_dwordx4 v[34:37], v1, s[24:25]
	global_load_dwordx4 v[38:41], v1, s[26:27]
	s_add_u32 s24, s24, 0x1000
	s_addc_u32 s25, s25, 0
	s_add_u32 s26, s26, 0x1000
	s_addc_u32 s27, s27, 0
.Lsc_pl3:
	s_add_u32 s38, s45, 4
	s_cmp_lt_u32 s38, s49
	s_cbranch_scc0 .Lsc_pl4
	global_load_dwordx4 v[42:45], v1, s[24:25]
	global_load_dwordx4 v[46:49], v1, s[26:27]
	s_add_u32 s24, s24, 0x1000
	s_addc_u32 s25, s25, 0
	s_add_u32 s26, s26, 0x1000
	s_addc_u32 s27, s27, 0
.Lsc_pl4:
	s_add_u32 s38, s45, 5
	s_cmp_lt_u32 s38, s49
	s_cbranch_scc0 .Lsc_pl5
	global_load_dwordx4 v[50:53], v1, s[24:25]
	global_load_dwordx4 v[54:57], v1, s[26:27]
	s_add_u32 s24, s24, 0x1000
	s_addc_u32 s25, s25, 0
	s_add_u32 s26, s26, 0x1000
	s_addc_u32 s27, s27, 0
.Lsc_pl5:
	s_add_u32 s38, s45, 6
	s_cmp_lt_u32 s38, s49
	s_cbranch_scc0 .Lsc_pl6
	global_load_dwordx4 v[58:61], v1, s[24:25]
	global_load_dwordx4 v[62:65], v1, s[26:27]
	s_add_u32 s24, s24, 0x1000
	s_addc_u32 s25, s25, 0
	s_add_u32 s26, s26, 0x1000
	s_addc_u32 s27, s27, 0
.Lsc_pl6:
	s_add_u32 s38, s45, 7
	s_cmp_lt_u32 s38, s49
	s_cbranch_scc0 .Lsc_pl7
	global_load_dwordx4 v[66:69], v1, s[24:25]
	global_load_dwordx4 v[70:73], v1, s[26:27]
	s_add_u32 s24, s24, 0x1000
	s_addc_u32 s25, s25, 0
	s_add_u32 s26, s26, 0x1000
	s_addc_u32 s27, s27, 0
.Lsc_pl7:
	s_waitcnt vmcnt(0)
	s_add_u32 s38, s45, 0
	s_cmp_lt_u32 s38, s49
	s_cbranch_scc0 .Lsc_pf0
	v_fma_f32 v4, v4, v10, v14
	v_fma_f32 v5, v5, v11, v15
	v_fma_f32 v6, v6, v12, v16
	v_fma_f32 v7, v7, v13, v17
.Lsc_pf0:
	s_add_u32 s38, s45, 1
	s_cmp_lt_u32 s38, s49
	s_cbranch_scc0 .Lsc_pf1
	v_fma_f32 v4, v4, v18, v22
	v_fma_f32 v5, v5, v19, v23
	v_fma_f32 v6, v6, v20, v24
	v_fma_f32 v7, v7, v21, v25
.Lsc_pf1:
	s_add_u32 s38, s45, 2
	s_cmp_lt_u32 s38, s49
	s_cbranch_scc0 .Lsc_pf2
	v_fma_f32 v4, v4, v26, v30
	v_fma_f32 v5, v5, v27, v31
	v_fma_f32 v6, v6, v28, v32
	v_fma_f32 v7, v7, v29, v33
.Lsc_pf2:
	s_add_u32 s38, s45, 3
	s_cmp_lt_u32 s38, s49
	s_cbranch_scc0 .Lsc_pf3
	v_fma_f32 v4, v4, v34, v38
	v_fma_f32 v5, v5, v35, v39
	v_fma_f32 v6, v6, v36, v40
	v_fma_f32 v7, v7, v37, v41
.Lsc_pf3:
	s_add_u32 s38, s45, 4
	s_cmp_lt_u32 s38, s49
	s_cbranch_scc0 .Lsc_pf4
	v_fma_f32 v4, v4, v42, v46
	v_fma_f32 v5, v5, v43, v47
	v_fma_f32 v6, v6, v44, v48
	v_fma_f32 v7, v7, v45, v49
.Lsc_pf4:
	s_add_u32 s38, s45, 5
	s_cmp_lt_u32 s38, s49
	s_cbranch_scc0 .Lsc_pf5
	v_fma_f32 v4, v4, v50, v54
	v_fma_f32 v5, v5, v51, v55
	v_fma_f32 v6, v6, v52, v56
	v_fma_f32 v7, v7, v53, v57
.Lsc_pf5:
	s_add_u32 s38, s45, 6
	s_cmp_lt_u32 s38, s49
	s_cbranch_scc0 .Lsc_pf6
	v_fma_f32 v4, v4, v58, v62
	v_fma_f32 v5, v5, v59, v63
	v_fma_f32 v6, v6, v60, v64
	v_fma_f32 v7, v7, v61, v65
.Lsc_pf6:
	s_add_u32 s38, s45, 7
	s_cmp_lt_u32 s38, s49
	s_cbranch_scc0 .Lsc_pf7
	v_fma_f32 v4, v4, v66, v70
	v_fma_f32 v5, v5, v67, v71
	v_fma_f32 v6, v6, v68, v72
	v_fma_f32 v7, v7, v69, v73
.Lsc_pf7:
	s_add_u32 s45, s45, 8
	s_branch .Lsc_pre
.Lsc_predone:
	s_lshl_b32 s39, s48, 11
	s_lshl_b32 s38, s49, 5
	s_add_u32 s39, s39, s38
	v_readlane_b32 s2, v255, 29
	v_readlane_b32 s3, v255, 30
	v_readlane_b32 s4, v255, 31
	v_readlane_b32 s5, v255, 32
	v_readlane_b32 s6, v255, 17
	v_readlane_b32 s7, v255, 18
	v_readlane_b32 s34, v255, 37
	v_readlane_b32 s35, v255, 38
	s_lshl_b32 s38, s39, 12
	s_add_u32 s2, s2, s38
	s_addc_u32 s3, s3, 0
	s_add_u32 s4, s4, s38
	s_addc_u32 s5, s5, 0
	s_mul_i32 s38, s39, 0x2500
	s_mul_hi_u32 s40, s39, 0x2500
	s_add_u32 s6, s6, s38
	s_addc_u32 s7, s7, s40
	s_add_u32 s6, s6, 0x1c30
	s_addc_u32 s7, s7, 0
	s_lshl_b32 s38, s39, 11
	s_add_u32 s34, s34, s38
	s_addc_u32 s35, s35, 0
	s_mov_b32 s41, 0
; DEV unsigned pack2(float a, float b) { float2v v = {a, b}; return __builtin_bit_cast(unsigned, __builtin_convertvector(v, bf16x2v)); }
; DEV float bflo(unsigned u) { return __uint_as_float(u << 16); }
; DEV float bfhi(unsigned u) { return __uint_as_float(u & 0xffff0000u); }
; DEV float gelu_exact(float v) { return 0.5f * v * (1.f + erff(v * 0.7071067811865476f)); }
; DEV void ph_scan2(const Params& p, int item) {
;     ...
; #pragma unroll 8
;   for (int t = 0; t < CHL; ++t) {
;     float4 a = *(const float4*)(p.a_arr + (row0 + t) * 1024 + ch);
;     float4 bb = *(const float4*)(p.b_arr + (row0 + t) * 1024 + ch);
;     u32x2 xg = *(const u32x2*)(p.z + (row0 + t) * ZLD + CXG + ch);
;     H[0] = a.x * H[0] + bb.x; H[1] = a.y * H[1] + bb.y; H[2] = a.z * H[2] + bb.z; H[3] = a.w * H[3] + bb.w;
;     u32x2 pk;
;     pk[0] = pack2(gelu_exact(bflo(xg[0])) * H[0], gelu_exact(bfhi(xg[0])) * H[1]);
;     pk[1] = pack2(gelu_exact(bflo(xg[1])) * H[2], gelu_exact(bfhi(xg[1])) * H[3]);
;     *(u32x2*)(p.orn + (row0 + t) * 1024 + ch) = pk;
;   }
.Lsc_main:
	global_load_dwordx4 v[80:83], v1, s[2:3]
	global_load_dwordx4 v[84:87], v1, s[4:5]
	global_load_dwordx2 v[88:89], v2, s[6:7]
	s_add_u32 s2, s2, 0x1000
	s_addc_u32 s3, s3, 0
	s_add_u32 s4, s4, 0x1000
	s_addc_u32 s5, s5, 0
	s_add_u32 s6, s6, 0x2500
	s_addc_u32 s7, s7, 0
	global_load_dwordx4 v[90:93], v1, s[2:3]
	global_load_dwordx4 v[94:97], v1, s[4:5]
	global_load_dwordx2 v[98:99], v2, s[6:7]
	s_add_u32 s2, s2, 0x1000
	s_addc_u32 s3, s3, 0
	s_add_u32 s4, s4, 0x1000
	s_addc_u32 s5, s5, 0
	s_add_u32 s6, s6, 0x2500
	s_addc_u32 s7, s7, 0
	global_load_dwordx4 v[100:103], v1, s[2:3]
	global_load_dwordx4 v[104:107], v1, s[4:5]
	global_load_dwordx2 v[108:109], v2, s[6:7]
	s_add_u32 s2, s2, 0x1000
	s_addc_u32 s3, s3, 0
	s_add_u32 s4, s4, 0x1000
	s_addc_u32 s5, s5, 0
	s_add_u32 s6, s6, 0x2500
	s_addc_u32 s7, s7, 0
	global_load_dwordx4 v[110:113], v1, s[2:3]
	global_load_dwordx4 v[114:117], v1, s[4:5]
	global_load_dwordx2 v[118:119], v2, s[6:7]
	s_add_u32 s2, s2, 0x1000
	s_addc_u32 s3, s3, 0
	s_add_u32 s4, s4, 0x1000
	s_addc_u32 s5, s5, 0
	s_add_u32 s6, s6, 0x2500
	s_addc_u32 s7, s7, 0
	global_load_dwordx4 v[120:123], v1, s[2:3]
	global_load_dwordx4 v[124:127], v1, s[4:5]
	global_load_dwordx2 v[128:129], v2, s[6:7]
	s_add_u32 s2, s2, 0x1000
	s_addc_u32 s3, s3, 0
	s_add_u32 s4, s4, 0x1000
	s_addc_u32 s5, s5, 0
	s_add_u32 s6, s6, 0x2500
	s_addc_u32 s7, s7, 0
	global_load_dwordx4 v[130:133], v1, s[2:3]
	global_load_dwordx4 v[134:137], v1, s[4:5]
	global_load_dwordx2 v[138:139], v2, s[6:7]
	s_add_u32 s2, s2, 0x1000
	s_addc_u32 s3, s3, 0
	s_add_u32 s4, s4, 0x1000
	s_addc_u32 s5, s5, 0
	s_add_u32 s6, s6, 0x2500
	s_addc_u32 s7, s7, 0
	global_load_dwordx4 v[140:143], v1, s[2:3]
	global_load_dwordx4 v[144:147], v1, s[4:5]
	global_load_dwordx2 v[148:149], v2, s[6:7]
	s_add_u32 s2, s2, 0x1000
	s_addc_u32 s3, s3, 0
	s_add_u32 s4, s4, 0x1000
	s_addc_u32 s5, s5, 0
	s_add_u32 s6, s6, 0x2500
	s_addc_u32 s7, s7, 0
	global_load_dwordx4 v[150:153], v1, s[2:3]
	global_load_dwordx4 v[154:157], v1, s[4:5]
	global_load_dwordx2 v[158:159], v2, s[6:7]
	s_add_u32 s2, s2, 0x1000
	s_addc_u32 s3, s3, 0
	s_add_u32 s4, s4, 0x1000
	s_addc_u32 s5, s5, 0
	s_add_u32 s6, s6, 0x2500
	s_addc_u32 s7, s7, 0
	s_waitcnt vmcnt(21)
	v_fma_f32 v4, v80, v4, v84
	v_fma_f32 v5, v81, v5, v85
	v_fma_f32 v6, v82, v6, v86
	v_fma_f32 v7, v83, v7, v87
	v_lshlrev_b32_e32 v168, 16, v88
	v_and_b32_e32 v169, 0xffff0000, v88
	v_lshlrev_b32_e32 v170, 16, v89
	v_and_b32_e32 v171, 0xffff0000, v89
	v_mul_f32_e32 v160, 0x3f3504f3, v168
	v_mul_f32_e32 v161, v160, v160
	v_fmamk_f32 v162, v161, 0xba1345e1, v8
	v_fmaak_f32 v162, v161, v162, 0xbcdac9b8
	v_fmaak_f32 v162, v161, v162, 0x3de703be
	v_fmaak_f32 v162, v161, v162, 0xbec09330
	v_fmaak_f32 v161, v161, v162, 0x3e0375d0
	v_fma_f32 v165, |v160|, v161, |v160|
	v_fma_f32 v161, |v160|, s72, v9
	v_fma_f32 v161, |v160|, v161, s73
	v_fma_f32 v161, |v160|, v161, s74
	v_fma_f32 v161, |v160|, v161, s75
	v_fma_f32 v161, |v160|, v161, s76
	v_fma_f32 v161, |v160|, v161, s77
	v_fma_f32 v161, |v160|, v161, |v160|
	v_mul_f32_e32 v162, 0xbfb8aa3b, v161
	v_fma_f32 v163, v161, s78, -v162
	v_rndne_f32_e32 v164, v162
	v_fmac_f32_e32 v163, 0xb2a5705f, v161
	v_sub_f32_e32 v162, v162, v164
	v_add_f32_e32 v162, v162, v163
	v_cvt_i32_f32_e32 v163, v164
	v_exp_f32_e32 v162, v162
	v_cmp_nlt_f32_e32 vcc, s79, v161
	v_ldexp_f32 v162, v162, v163
	s_nop 0
	v_cndmask_b32_e32 v162, 0, v162, vcc
	v_cmp_ngt_f32_e32 vcc, s80, v161
	s_nop 1
	v_cndmask_b32_e32 v161, v3, v162, vcc
	v_sub_f32_e32 v166, 1.0, v161
	v_cmp_lt_f32_e64 vcc, |v160|, 1.0
	s_nop 1
	v_cndmask_b32_e32 v165, v166, v165, vcc
	v_bfi_b32 v165, s81, v165, v160
	v_mul_f32_e32 v161, 0.5, v168
	v_add_f32_e32 v165, 1.0, v165
	v_mul_f32_e32 v161, v161, v165
	v_mul_f32_e32 v176, v161, v4
	v_mul_f32_e32 v160, 0x3f3504f3, v169
	v_mul_f32_e32 v161, v160, v160
	v_fmamk_f32 v162, v161, 0xba1345e1, v8
	v_fmaak_f32 v162, v161, v162, 0xbcdac9b8
	v_fmaak_f32 v162, v161, v162, 0x3de703be
	v_fmaak_f32 v162, v161, v162, 0xbec09330
	v_fmaak_f32 v161, v161, v162, 0x3e0375d0
	v_fma_f32 v165, |v160|, v161, |v160|
	v_fma_f32 v161, |v160|, s72, v9
	v_fma_f32 v161, |v160|, v161, s73
	v_fma_f32 v161, |v160|, v161, s74
	v_fma_f32 v161, |v160|, v161, s75
	v_fma_f32 v161, |v160|, v161, s76
	v_fma_f32 v161, |v160|, v161, s77
	v_fma_f32 v161, |v160|, v161, |v160|
	v_mul_f32_e32 v162, 0xbfb8aa3b, v161
	v_fma_f32 v163, v161, s78, -v162
	v_rndne_f32_e32 v164, v162
	v_fmac_f32_e32 v163, 0xb2a5705f, v161
	v_sub_f32_e32 v162, v162, v164
	v_add_f32_e32 v162, v162, v163
	v_cvt_i32_f32_e32 v163, v164
	v_exp_f32_e32 v162, v162
	v_cmp_nlt_f32_e32 vcc, s79, v161
	v_ldexp_f32 v162, v162, v163
	s_nop 0
	v_cndmask_b32_e32 v162, 0, v162, vcc
	v_cmp_ngt_f32_e32 vcc, s80, v161
	s_nop 1
	v_cndmask_b32_e32 v161, v3, v162, vcc
	v_sub_f32_e32 v166, 1.0, v161
	v_cmp_lt_f32_e64 vcc, |v160|, 1.0
	s_nop 1
	v_cndmask_b32_e32 v165, v166, v165, vcc
	v_bfi_b32 v165, s81, v165, v160
	v_mul_f32_e32 v161, 0.5, v169
	v_add_f32_e32 v165, 1.0, v165
	v_mul_f32_e32 v161, v161, v165
	v_mul_f32_e32 v177, v161, v5
	v_mul_f32_e32 v160, 0x3f3504f3, v170
	v_mul_f32_e32 v161, v160, v160
	v_fmamk_f32 v162, v161, 0xba1345e1, v8
	v_fmaak_f32 v162, v161, v162, 0xbcdac9b8
	v_fmaak_f32 v162, v161, v162, 0x3de703be
	v_fmaak_f32 v162, v161, v162, 0xbec09330
	v_fmaak_f32 v161, v161, v162, 0x3e0375d0
	v_fma_f32 v165, |v160|, v161, |v160|
	v_fma_f32 v161, |v160|, s72, v9
	v_fma_f32 v161, |v160|, v161, s73
	v_fma_f32 v161, |v160|, v161, s74
	v_fma_f32 v161, |v160|, v161, s75
	v_fma_f32 v161, |v160|, v161, s76
	v_fma_f32 v161, |v160|, v161, s77
	v_fma_f32 v161, |v160|, v161, |v160|
	v_mul_f32_e32 v162, 0xbfb8aa3b, v161
; DEV unsigned pack2(float a, float b) { float2v v = {a, b}; return __builtin_bit_cast(unsigned, __builtin_convertvector(v, bf16x2v)); }
; DEV float bflo(unsigned u) { return __uint_as_float(u << 16); }
; DEV float bfhi(unsigned u) { return __uint_as_float(u & 0xffff0000u); }
; DEV float gelu_exact(float v) { return 0.5f * v * (1.f + erff(v * 0.7071067811865476f)); }
; DEV void ph_scan2(const Params& p, int item) {
;     ...
; #pragma unroll 8
;   for (int t = 0; t < CHL; ++t) {
;     float4 a = *(const float4*)(p.a_arr + (row0 + t) * 1024 + ch);
;     float4 bb = *(const float4*)(p.b_arr + (row0 + t) * 1024 + ch);
;     u32x2 xg = *(const u32x2*)(p.z + (row0 + t) * ZLD + CXG + ch);
;     H[0] = a.x * H[0] + bb.x; H[1] = a.y * H[1] + bb.y; H[2] = a.z * H[2] + bb.z; H[3] = a.w * H[3] + bb.w;
;     u32x2 pk;
;     pk[0] = pack2(gelu_exact(bflo(xg[0])) * H[0], gelu_exact(bfhi(xg[0])) * H[1]);
;     pk[1] = pack2(gelu_exact(bflo(xg[1])) * H[2], gelu_exact(bfhi(xg[1])) * H[3]);
;     *(u32x2*)(p.orn + (row0 + t) * 1024 + ch) = pk;
;   }
	v_fma_f32 v163, v161, s78, -v162
	v_rndne_f32_e32 v164, v162
	v_fmac_f32_e32 v163, 0xb2a5705f, v161
	v_sub_f32_e32 v162, v162, v164
	v_add_f32_e32 v162, v162, v163
	v_cvt_i32_f32_e32 v163, v164
	v_exp_f32_e32 v162, v162
	v_cmp_nlt_f32_e32 vcc, s79, v161
	v_ldexp_f32 v162, v162, v163
	s_nop 0
	v_cndmask_b32_e32 v162, 0, v162, vcc
	v_cmp_ngt_f32_e32 vcc, s80, v161
	s_nop 1
	v_cndmask_b32_e32 v161, v3, v162, vcc
	v_sub_f32_e32 v166, 1.0, v161
	v_cmp_lt_f32_e64 vcc, |v160|, 1.0
	s_nop 1
	v_cndmask_b32_e32 v165, v166, v165, vcc
	v_bfi_b32 v165, s81, v165, v160
	v_mul_f32_e32 v161, 0.5, v170
	v_add_f32_e32 v165, 1.0, v165
	v_mul_f32_e32 v161, v161, v165
	v_mul_f32_e32 v178, v161, v6
	v_mul_f32_e32 v160, 0x3f3504f3, v171
	v_mul_f32_e32 v161, v160, v160
	v_fmamk_f32 v162, v161, 0xba1345e1, v8
	v_fmaak_f32 v162, v161, v162, 0xbcdac9b8
	v_fmaak_f32 v162, v161, v162, 0x3de703be
	v_fmaak_f32 v162, v161, v162, 0xbec09330
	v_fmaak_f32 v161, v161, v162, 0x3e0375d0
	v_fma_f32 v165, |v160|, v161, |v160|
	v_fma_f32 v161, |v160|, s72, v9
	v_fma_f32 v161, |v160|, v161, s73
	v_fma_f32 v161, |v160|, v161, s74
	v_fma_f32 v161, |v160|, v161, s75
	v_fma_f32 v161, |v160|, v161, s76
	v_fma_f32 v161, |v160|, v161, s77
	v_fma_f32 v161, |v160|, v161, |v160|
	v_mul_f32_e32 v162, 0xbfb8aa3b, v161
	v_fma_f32 v163, v161, s78, -v162
	v_rndne_f32_e32 v164, v162
	v_fmac_f32_e32 v163, 0xb2a5705f, v161
	v_sub_f32_e32 v162, v162, v164
	v_add_f32_e32 v162, v162, v163
	v_cvt_i32_f32_e32 v163, v164
	v_exp_f32_e32 v162, v162
	v_cmp_nlt_f32_e32 vcc, s79, v161
	v_ldexp_f32 v162, v162, v163
	s_nop 0
	v_cndmask_b32_e32 v162, 0, v162, vcc
	v_cmp_ngt_f32_e32 vcc, s80, v161
	s_nop 1
	v_cndmask_b32_e32 v161, v3, v162, vcc
	v_sub_f32_e32 v166, 1.0, v161
	v_cmp_lt_f32_e64 vcc, |v160|, 1.0
	s_nop 1
	v_cndmask_b32_e32 v165, v166, v165, vcc
	v_bfi_b32 v165, s81, v165, v160
	v_mul_f32_e32 v161, 0.5, v171
	v_add_f32_e32 v165, 1.0, v165
	v_mul_f32_e32 v161, v161, v165
	v_mul_f32_e32 v179, v161, v7
	v_cvt_pk_bf16_f32 v180, v176, v177
	v_cvt_pk_bf16_f32 v181, v178, v179
	global_store_dwordx2 v2, v[180:181], s[34:35]
	s_add_u32 s34, s34, 0x800
	s_addc_u32 s35, s35, 0
	s_waitcnt vmcnt(19)
	v_fma_f32 v4, v90, v4, v94
	v_fma_f32 v5, v91, v5, v95
	v_fma_f32 v6, v92, v6, v96
	v_fma_f32 v7, v93, v7, v97
	v_lshlrev_b32_e32 v168, 16, v98
	v_and_b32_e32 v169, 0xffff0000, v98
	v_lshlrev_b32_e32 v170, 16, v99
	v_and_b32_e32 v171, 0xffff0000, v99
	v_mul_f32_e32 v160, 0x3f3504f3, v168
	v_mul_f32_e32 v161, v160, v160
	v_fmamk_f32 v162, v161, 0xba1345e1, v8
	v_fmaak_f32 v162, v161, v162, 0xbcdac9b8
	v_fmaak_f32 v162, v161, v162, 0x3de703be
	v_fmaak_f32 v162, v161, v162, 0xbec09330
	v_fmaak_f32 v161, v161, v162, 0x3e0375d0
	v_fma_f32 v165, |v160|, v161, |v160|
	v_fma_f32 v161, |v160|, s72, v9
	v_fma_f32 v161, |v160|, v161, s73
	v_fma_f32 v161, |v160|, v161, s74
	v_fma_f32 v161, |v160|, v161, s75
	v_fma_f32 v161, |v160|, v161, s76
	v_fma_f32 v161, |v160|, v161, s77
	v_fma_f32 v161, |v160|, v161, |v160|
	v_mul_f32_e32 v162, 0xbfb8aa3b, v161
	v_fma_f32 v163, v161, s78, -v162
	v_rndne_f32_e32 v164, v162
	v_fmac_f32_e32 v163, 0xb2a5705f, v161
	v_sub_f32_e32 v162, v162, v164
	v_add_f32_e32 v162, v162, v163
	v_cvt_i32_f32_e32 v163, v164
	v_exp_f32_e32 v162, v162
	v_cmp_nlt_f32_e32 vcc, s79, v161
	v_ldexp_f32 v162, v162, v163
	s_nop 0
	v_cndmask_b32_e32 v162, 0, v162, vcc
	v_cmp_ngt_f32_e32 vcc, s80, v161
	s_nop 1
	v_cndmask_b32_e32 v161, v3, v162, vcc
	v_sub_f32_e32 v166, 1.0, v161
	v_cmp_lt_f32_e64 vcc, |v160|, 1.0
	s_nop 1
	v_cndmask_b32_e32 v165, v166, v165, vcc
	v_bfi_b32 v165, s81, v165, v160
	v_mul_f32_e32 v161, 0.5, v168
	v_add_f32_e32 v165, 1.0, v165
	v_mul_f32_e32 v161, v161, v165
	v_mul_f32_e32 v176, v161, v4
	v_mul_f32_e32 v160, 0x3f3504f3, v169
	v_mul_f32_e32 v161, v160, v160
	v_fmamk_f32 v162, v161, 0xba1345e1, v8
	v_fmaak_f32 v162, v161, v162, 0xbcdac9b8
	v_fmaak_f32 v162, v161, v162, 0x3de703be
	v_fmaak_f32 v162, v161, v162, 0xbec09330
	v_fmaak_f32 v161, v161, v162, 0x3e0375d0
	v_fma_f32 v165, |v160|, v161, |v160|
	v_fma_f32 v161, |v160|, s72, v9
	v_fma_f32 v161, |v160|, v161, s73
	v_fma_f32 v161, |v160|, v161, s74
	v_fma_f32 v161, |v160|, v161, s75
	v_fma_f32 v161, |v160|, v161, s76
	v_fma_f32 v161, |v160|, v161, s77
	v_fma_f32 v161, |v160|, v161, |v160|
	v_mul_f32_e32 v162, 0xbfb8aa3b, v161
	v_fma_f32 v163, v161, s78, -v162
	v_rndne_f32_e32 v164, v162
	v_fmac_f32_e32 v163, 0xb2a5705f, v161
	v_sub_f32_e32 v162, v162, v164
	v_add_f32_e32 v162, v162, v163
	v_cvt_i32_f32_e32 v163, v164
	v_exp_f32_e32 v162, v162
	v_cmp_nlt_f32_e32 vcc, s79, v161
	v_ldexp_f32 v162, v162, v163
	s_nop 0
	v_cndmask_b32_e32 v162, 0, v162, vcc
	v_cmp_ngt_f32_e32 vcc, s80, v161
	s_nop 1
	v_cndmask_b32_e32 v161, v3, v162, vcc
	v_sub_f32_e32 v166, 1.0, v161
	v_cmp_lt_f32_e64 vcc, |v160|, 1.0
	s_nop 1
	v_cndmask_b32_e32 v165, v166, v165, vcc
	v_bfi_b32 v165, s81, v165, v160
	v_mul_f32_e32 v161, 0.5, v169
	v_add_f32_e32 v165, 1.0, v165
	v_mul_f32_e32 v161, v161, v165
	v_mul_f32_e32 v177, v161, v5
	v_mul_f32_e32 v160, 0x3f3504f3, v170
	v_mul_f32_e32 v161, v160, v160
	v_fmamk_f32 v162, v161, 0xba1345e1, v8
	v_fmaak_f32 v162, v161, v162, 0xbcdac9b8
	v_fmaak_f32 v162, v161, v162, 0x3de703be
	v_fmaak_f32 v162, v161, v162, 0xbec09330
	v_fmaak_f32 v161, v161, v162, 0x3e0375d0
	v_fma_f32 v165, |v160|, v161, |v160|
	v_fma_f32 v161, |v160|, s72, v9
	v_fma_f32 v161, |v160|, v161, s73
	v_fma_f32 v161, |v160|, v161, s74
	v_fma_f32 v161, |v160|, v161, s75
	v_fma_f32 v161, |v160|, v161, s76
	v_fma_f32 v161, |v160|, v161, s77
	v_fma_f32 v161, |v160|, v161, |v160|
	v_mul_f32_e32 v162, 0xbfb8aa3b, v161
	v_fma_f32 v163, v161, s78, -v162
	v_rndne_f32_e32 v164, v162
; DEV unsigned pack2(float a, float b) { float2v v = {a, b}; return __builtin_bit_cast(unsigned, __builtin_convertvector(v, bf16x2v)); }
; DEV float bflo(unsigned u) { return __uint_as_float(u << 16); }
; DEV float bfhi(unsigned u) { return __uint_as_float(u & 0xffff0000u); }
; DEV float gelu_exact(float v) { return 0.5f * v * (1.f + erff(v * 0.7071067811865476f)); }
; DEV void ph_scan2(const Params& p, int item) {
;     ...
; #pragma unroll 8
;   for (int t = 0; t < CHL; ++t) {
;     float4 a = *(const float4*)(p.a_arr + (row0 + t) * 1024 + ch);
;     float4 bb = *(const float4*)(p.b_arr + (row0 + t) * 1024 + ch);
;     u32x2 xg = *(const u32x2*)(p.z + (row0 + t) * ZLD + CXG + ch);
;     H[0] = a.x * H[0] + bb.x; H[1] = a.y * H[1] + bb.y; H[2] = a.z * H[2] + bb.z; H[3] = a.w * H[3] + bb.w;
;     u32x2 pk;
;     pk[0] = pack2(gelu_exact(bflo(xg[0])) * H[0], gelu_exact(bfhi(xg[0])) * H[1]);
;     pk[1] = pack2(gelu_exact(bflo(xg[1])) * H[2], gelu_exact(bfhi(xg[1])) * H[3]);
;     *(u32x2*)(p.orn + (row0 + t) * 1024 + ch) = pk;
;   }
	v_fmac_f32_e32 v163, 0xb2a5705f, v161
	v_sub_f32_e32 v162, v162, v164
	v_add_f32_e32 v162, v162, v163
	v_cvt_i32_f32_e32 v163, v164
	v_exp_f32_e32 v162, v162
	v_cmp_nlt_f32_e32 vcc, s79, v161
	v_ldexp_f32 v162, v162, v163
	s_nop 0
	v_cndmask_b32_e32 v162, 0, v162, vcc
	v_cmp_ngt_f32_e32 vcc, s80, v161
	s_nop 1
	v_cndmask_b32_e32 v161, v3, v162, vcc
	v_sub_f32_e32 v166, 1.0, v161
	v_cmp_lt_f32_e64 vcc, |v160|, 1.0
	s_nop 1
	v_cndmask_b32_e32 v165, v166, v165, vcc
	v_bfi_b32 v165, s81, v165, v160
	v_mul_f32_e32 v161, 0.5, v170
	v_add_f32_e32 v165, 1.0, v165
	v_mul_f32_e32 v161, v161, v165
	v_mul_f32_e32 v178, v161, v6
	v_mul_f32_e32 v160, 0x3f3504f3, v171
	v_mul_f32_e32 v161, v160, v160
	v_fmamk_f32 v162, v161, 0xba1345e1, v8
	v_fmaak_f32 v162, v161, v162, 0xbcdac9b8
	v_fmaak_f32 v162, v161, v162, 0x3de703be
	v_fmaak_f32 v162, v161, v162, 0xbec09330
	v_fmaak_f32 v161, v161, v162, 0x3e0375d0
	v_fma_f32 v165, |v160|, v161, |v160|
	v_fma_f32 v161, |v160|, s72, v9
	v_fma_f32 v161, |v160|, v161, s73
	v_fma_f32 v161, |v160|, v161, s74
	v_fma_f32 v161, |v160|, v161, s75
	v_fma_f32 v161, |v160|, v161, s76
	v_fma_f32 v161, |v160|, v161, s77
	v_fma_f32 v161, |v160|, v161, |v160|
	v_mul_f32_e32 v162, 0xbfb8aa3b, v161
	v_fma_f32 v163, v161, s78, -v162
	v_rndne_f32_e32 v164, v162
	v_fmac_f32_e32 v163, 0xb2a5705f, v161
	v_sub_f32_e32 v162, v162, v164
	v_add_f32_e32 v162, v162, v163
	v_cvt_i32_f32_e32 v163, v164
	v_exp_f32_e32 v162, v162
	v_cmp_nlt_f32_e32 vcc, s79, v161
	v_ldexp_f32 v162, v162, v163
	s_nop 0
	v_cndmask_b32_e32 v162, 0, v162, vcc
	v_cmp_ngt_f32_e32 vcc, s80, v161
	s_nop 1
	v_cndmask_b32_e32 v161, v3, v162, vcc
	v_sub_f32_e32 v166, 1.0, v161
	v_cmp_lt_f32_e64 vcc, |v160|, 1.0
	s_nop 1
	v_cndmask_b32_e32 v165, v166, v165, vcc
	v_bfi_b32 v165, s81, v165, v160
	v_mul_f32_e32 v161, 0.5, v171
	v_add_f32_e32 v165, 1.0, v165
	v_mul_f32_e32 v161, v161, v165
	v_mul_f32_e32 v179, v161, v7
	v_cvt_pk_bf16_f32 v180, v176, v177
	v_cvt_pk_bf16_f32 v181, v178, v179
	global_store_dwordx2 v2, v[180:181], s[34:35]
	s_add_u32 s34, s34, 0x800
	s_addc_u32 s35, s35, 0
	s_waitcnt vmcnt(17)
	v_fma_f32 v4, v100, v4, v104
	v_fma_f32 v5, v101, v5, v105
	v_fma_f32 v6, v102, v6, v106
	v_fma_f32 v7, v103, v7, v107
	v_lshlrev_b32_e32 v168, 16, v108
	v_and_b32_e32 v169, 0xffff0000, v108
	v_lshlrev_b32_e32 v170, 16, v109
	v_and_b32_e32 v171, 0xffff0000, v109
	v_mul_f32_e32 v160, 0x3f3504f3, v168
	v_mul_f32_e32 v161, v160, v160
	v_fmamk_f32 v162, v161, 0xba1345e1, v8
	v_fmaak_f32 v162, v161, v162, 0xbcdac9b8
	v_fmaak_f32 v162, v161, v162, 0x3de703be
	v_fmaak_f32 v162, v161, v162, 0xbec09330
	v_fmaak_f32 v161, v161, v162, 0x3e0375d0
	v_fma_f32 v165, |v160|, v161, |v160|
	v_fma_f32 v161, |v160|, s72, v9
	v_fma_f32 v161, |v160|, v161, s73
	v_fma_f32 v161, |v160|, v161, s74
	v_fma_f32 v161, |v160|, v161, s75
	v_fma_f32 v161, |v160|, v161, s76
	v_fma_f32 v161, |v160|, v161, s77
	v_fma_f32 v161, |v160|, v161, |v160|
	v_mul_f32_e32 v162, 0xbfb8aa3b, v161
	v_fma_f32 v163, v161, s78, -v162
	v_rndne_f32_e32 v164, v162
	v_fmac_f32_e32 v163, 0xb2a5705f, v161
	v_sub_f32_e32 v162, v162, v164
	v_add_f32_e32 v162, v162, v163
	v_cvt_i32_f32_e32 v163, v164
	v_exp_f32_e32 v162, v162
	v_cmp_nlt_f32_e32 vcc, s79, v161
	v_ldexp_f32 v162, v162, v163
	s_nop 0
	v_cndmask_b32_e32 v162, 0, v162, vcc
	v_cmp_ngt_f32_e32 vcc, s80, v161
	s_nop 1
	v_cndmask_b32_e32 v161, v3, v162, vcc
	v_sub_f32_e32 v166, 1.0, v161
	v_cmp_lt_f32_e64 vcc, |v160|, 1.0
	s_nop 1
	v_cndmask_b32_e32 v165, v166, v165, vcc
	v_bfi_b32 v165, s81, v165, v160
	v_mul_f32_e32 v161, 0.5, v168
	v_add_f32_e32 v165, 1.0, v165
	v_mul_f32_e32 v161, v161, v165
	v_mul_f32_e32 v176, v161, v4
	v_mul_f32_e32 v160, 0x3f3504f3, v169
	v_mul_f32_e32 v161, v160, v160
	v_fmamk_f32 v162, v161, 0xba1345e1, v8
	v_fmaak_f32 v162, v161, v162, 0xbcdac9b8
	v_fmaak_f32 v162, v161, v162, 0x3de703be
	v_fmaak_f32 v162, v161, v162, 0xbec09330
	v_fmaak_f32 v161, v161, v162, 0x3e0375d0
	v_fma_f32 v165, |v160|, v161, |v160|
	v_fma_f32 v161, |v160|, s72, v9
	v_fma_f32 v161, |v160|, v161, s73
	v_fma_f32 v161, |v160|, v161, s74
	v_fma_f32 v161, |v160|, v161, s75
	v_fma_f32 v161, |v160|, v161, s76
	v_fma_f32 v161, |v160|, v161, s77
	v_fma_f32 v161, |v160|, v161, |v160|
	v_mul_f32_e32 v162, 0xbfb8aa3b, v161
	v_fma_f32 v163, v161, s78, -v162
	v_rndne_f32_e32 v164, v162
	v_fmac_f32_e32 v163, 0xb2a5705f, v161
	v_sub_f32_e32 v162, v162, v164
	v_add_f32_e32 v162, v162, v163
	v_cvt_i32_f32_e32 v163, v164
	v_exp_f32_e32 v162, v162
	v_cmp_nlt_f32_e32 vcc, s79, v161
	v_ldexp_f32 v162, v162, v163
	s_nop 0
	v_cndmask_b32_e32 v162, 0, v162, vcc
	v_cmp_ngt_f32_e32 vcc, s80, v161
	s_nop 1
	v_cndmask_b32_e32 v161, v3, v162, vcc
	v_sub_f32_e32 v166, 1.0, v161
	v_cmp_lt_f32_e64 vcc, |v160|, 1.0
	s_nop 1
	v_cndmask_b32_e32 v165, v166, v165, vcc
	v_bfi_b32 v165, s81, v165, v160
	v_mul_f32_e32 v161, 0.5, v169
	v_add_f32_e32 v165, 1.0, v165
	v_mul_f32_e32 v161, v161, v165
	v_mul_f32_e32 v177, v161, v5
	v_mul_f32_e32 v160, 0x3f3504f3, v170
	v_mul_f32_e32 v161, v160, v160
	v_fmamk_f32 v162, v161, 0xba1345e1, v8
	v_fmaak_f32 v162, v161, v162, 0xbcdac9b8
	v_fmaak_f32 v162, v161, v162, 0x3de703be
	v_fmaak_f32 v162, v161, v162, 0xbec09330
	v_fmaak_f32 v161, v161, v162, 0x3e0375d0
	v_fma_f32 v165, |v160|, v161, |v160|
	v_fma_f32 v161, |v160|, s72, v9
	v_fma_f32 v161, |v160|, v161, s73
	v_fma_f32 v161, |v160|, v161, s74
	v_fma_f32 v161, |v160|, v161, s75
	v_fma_f32 v161, |v160|, v161, s76
	v_fma_f32 v161, |v160|, v161, s77
	v_fma_f32 v161, |v160|, v161, |v160|
	v_mul_f32_e32 v162, 0xbfb8aa3b, v161
	v_fma_f32 v163, v161, s78, -v162
	v_rndne_f32_e32 v164, v162
	v_fmac_f32_e32 v163, 0xb2a5705f, v161
; DEV unsigned pack2(float a, float b) { float2v v = {a, b}; return __builtin_bit_cast(unsigned, __builtin_convertvector(v, bf16x2v)); }
; DEV float bflo(unsigned u) { return __uint_as_float(u << 16); }
; DEV float bfhi(unsigned u) { return __uint_as_float(u & 0xffff0000u); }
; DEV float gelu_exact(float v) { return 0.5f * v * (1.f + erff(v * 0.7071067811865476f)); }
; DEV void ph_scan2(const Params& p, int item) {
;     ...
; #pragma unroll 8
;   for (int t = 0; t < CHL; ++t) {
;     float4 a = *(const float4*)(p.a_arr + (row0 + t) * 1024 + ch);
;     float4 bb = *(const float4*)(p.b_arr + (row0 + t) * 1024 + ch);
;     u32x2 xg = *(const u32x2*)(p.z + (row0 + t) * ZLD + CXG + ch);
;     H[0] = a.x * H[0] + bb.x; H[1] = a.y * H[1] + bb.y; H[2] = a.z * H[2] + bb.z; H[3] = a.w * H[3] + bb.w;
;     u32x2 pk;
;     pk[0] = pack2(gelu_exact(bflo(xg[0])) * H[0], gelu_exact(bfhi(xg[0])) * H[1]);
;     pk[1] = pack2(gelu_exact(bflo(xg[1])) * H[2], gelu_exact(bfhi(xg[1])) * H[3]);
;     *(u32x2*)(p.orn + (row0 + t) * 1024 + ch) = pk;
;   }
	v_sub_f32_e32 v162, v162, v164
	v_add_f32_e32 v162, v162, v163
	v_cvt_i32_f32_e32 v163, v164
	v_exp_f32_e32 v162, v162
	v_cmp_nlt_f32_e32 vcc, s79, v161
	v_ldexp_f32 v162, v162, v163
	s_nop 0
	v_cndmask_b32_e32 v162, 0, v162, vcc
	v_cmp_ngt_f32_e32 vcc, s80, v161
	s_nop 1
	v_cndmask_b32_e32 v161, v3, v162, vcc
	v_sub_f32_e32 v166, 1.0, v161
	v_cmp_lt_f32_e64 vcc, |v160|, 1.0
	s_nop 1
	v_cndmask_b32_e32 v165, v166, v165, vcc
	v_bfi_b32 v165, s81, v165, v160
	v_mul_f32_e32 v161, 0.5, v170
	v_add_f32_e32 v165, 1.0, v165
	v_mul_f32_e32 v161, v161, v165
	v_mul_f32_e32 v178, v161, v6
	v_mul_f32_e32 v160, 0x3f3504f3, v171
	v_mul_f32_e32 v161, v160, v160
	v_fmamk_f32 v162, v161, 0xba1345e1, v8
	v_fmaak_f32 v162, v161, v162, 0xbcdac9b8
	v_fmaak_f32 v162, v161, v162, 0x3de703be
	v_fmaak_f32 v162, v161, v162, 0xbec09330
	v_fmaak_f32 v161, v161, v162, 0x3e0375d0
	v_fma_f32 v165, |v160|, v161, |v160|
	v_fma_f32 v161, |v160|, s72, v9
	v_fma_f32 v161, |v160|, v161, s73
	v_fma_f32 v161, |v160|, v161, s74
	v_fma_f32 v161, |v160|, v161, s75
	v_fma_f32 v161, |v160|, v161, s76
	v_fma_f32 v161, |v160|, v161, s77
	v_fma_f32 v161, |v160|, v161, |v160|
	v_mul_f32_e32 v162, 0xbfb8aa3b, v161
	v_fma_f32 v163, v161, s78, -v162
	v_rndne_f32_e32 v164, v162
	v_fmac_f32_e32 v163, 0xb2a5705f, v161
	v_sub_f32_e32 v162, v162, v164
	v_add_f32_e32 v162, v162, v163
	v_cvt_i32_f32_e32 v163, v164
	v_exp_f32_e32 v162, v162
	v_cmp_nlt_f32_e32 vcc, s79, v161
	v_ldexp_f32 v162, v162, v163
	s_nop 0
	v_cndmask_b32_e32 v162, 0, v162, vcc
	v_cmp_ngt_f32_e32 vcc, s80, v161
	s_nop 1
	v_cndmask_b32_e32 v161, v3, v162, vcc
	v_sub_f32_e32 v166, 1.0, v161
	v_cmp_lt_f32_e64 vcc, |v160|, 1.0
	s_nop 1
	v_cndmask_b32_e32 v165, v166, v165, vcc
	v_bfi_b32 v165, s81, v165, v160
	v_mul_f32_e32 v161, 0.5, v171
	v_add_f32_e32 v165, 1.0, v165
	v_mul_f32_e32 v161, v161, v165
	v_mul_f32_e32 v179, v161, v7
	v_cvt_pk_bf16_f32 v180, v176, v177
	v_cvt_pk_bf16_f32 v181, v178, v179
	global_store_dwordx2 v2, v[180:181], s[34:35]
	s_add_u32 s34, s34, 0x800
	s_addc_u32 s35, s35, 0
	s_waitcnt vmcnt(15)
	v_fma_f32 v4, v110, v4, v114
	v_fma_f32 v5, v111, v5, v115
	v_fma_f32 v6, v112, v6, v116
	v_fma_f32 v7, v113, v7, v117
	v_lshlrev_b32_e32 v168, 16, v118
	v_and_b32_e32 v169, 0xffff0000, v118
	v_lshlrev_b32_e32 v170, 16, v119
	v_and_b32_e32 v171, 0xffff0000, v119
	v_mul_f32_e32 v160, 0x3f3504f3, v168
	v_mul_f32_e32 v161, v160, v160
	v_fmamk_f32 v162, v161, 0xba1345e1, v8
	v_fmaak_f32 v162, v161, v162, 0xbcdac9b8
	v_fmaak_f32 v162, v161, v162, 0x3de703be
	v_fmaak_f32 v162, v161, v162, 0xbec09330
	v_fmaak_f32 v161, v161, v162, 0x3e0375d0
	v_fma_f32 v165, |v160|, v161, |v160|
	v_fma_f32 v161, |v160|, s72, v9
	v_fma_f32 v161, |v160|, v161, s73
	v_fma_f32 v161, |v160|, v161, s74
	v_fma_f32 v161, |v160|, v161, s75
	v_fma_f32 v161, |v160|, v161, s76
	v_fma_f32 v161, |v160|, v161, s77
	v_fma_f32 v161, |v160|, v161, |v160|
	v_mul_f32_e32 v162, 0xbfb8aa3b, v161
	v_fma_f32 v163, v161, s78, -v162
	v_rndne_f32_e32 v164, v162
	v_fmac_f32_e32 v163, 0xb2a5705f, v161
	v_sub_f32_e32 v162, v162, v164
	v_add_f32_e32 v162, v162, v163
	v_cvt_i32_f32_e32 v163, v164
	v_exp_f32_e32 v162, v162
	v_cmp_nlt_f32_e32 vcc, s79, v161
	v_ldexp_f32 v162, v162, v163
	s_nop 0
	v_cndmask_b32_e32 v162, 0, v162, vcc
	v_cmp_ngt_f32_e32 vcc, s80, v161
	s_nop 1
	v_cndmask_b32_e32 v161, v3, v162, vcc
	v_sub_f32_e32 v166, 1.0, v161
	v_cmp_lt_f32_e64 vcc, |v160|, 1.0
	s_nop 1
	v_cndmask_b32_e32 v165, v166, v165, vcc
	v_bfi_b32 v165, s81, v165, v160
	v_mul_f32_e32 v161, 0.5, v168
	v_add_f32_e32 v165, 1.0, v165
	v_mul_f32_e32 v161, v161, v165
	v_mul_f32_e32 v176, v161, v4
	v_mul_f32_e32 v160, 0x3f3504f3, v169
	v_mul_f32_e32 v161, v160, v160
	v_fmamk_f32 v162, v161, 0xba1345e1, v8
	v_fmaak_f32 v162, v161, v162, 0xbcdac9b8
	v_fmaak_f32 v162, v161, v162, 0x3de703be
	v_fmaak_f32 v162, v161, v162, 0xbec09330
	v_fmaak_f32 v161, v161, v162, 0x3e0375d0
	v_fma_f32 v165, |v160|, v161, |v160|
	v_fma_f32 v161, |v160|, s72, v9
	v_fma_f32 v161, |v160|, v161, s73
	v_fma_f32 v161, |v160|, v161, s74
	v_fma_f32 v161, |v160|, v161, s75
	v_fma_f32 v161, |v160|, v161, s76
	v_fma_f32 v161, |v160|, v161, s77
	v_fma_f32 v161, |v160|, v161, |v160|
	v_mul_f32_e32 v162, 0xbfb8aa3b, v161
	v_fma_f32 v163, v161, s78, -v162
	v_rndne_f32_e32 v164, v162
	v_fmac_f32_e32 v163, 0xb2a5705f, v161
	v_sub_f32_e32 v162, v162, v164
	v_add_f32_e32 v162, v162, v163
	v_cvt_i32_f32_e32 v163, v164
	v_exp_f32_e32 v162, v162
	v_cmp_nlt_f32_e32 vcc, s79, v161
	v_ldexp_f32 v162, v162, v163
	s_nop 0
	v_cndmask_b32_e32 v162, 0, v162, vcc
	v_cmp_ngt_f32_e32 vcc, s80, v161
	s_nop 1
	v_cndmask_b32_e32 v161, v3, v162, vcc
	v_sub_f32_e32 v166, 1.0, v161
	v_cmp_lt_f32_e64 vcc, |v160|, 1.0
	s_nop 1
	v_cndmask_b32_e32 v165, v166, v165, vcc
	v_bfi_b32 v165, s81, v165, v160
	v_mul_f32_e32 v161, 0.5, v169
	v_add_f32_e32 v165, 1.0, v165
	v_mul_f32_e32 v161, v161, v165
	v_mul_f32_e32 v177, v161, v5
	v_mul_f32_e32 v160, 0x3f3504f3, v170
	v_mul_f32_e32 v161, v160, v160
	v_fmamk_f32 v162, v161, 0xba1345e1, v8
	v_fmaak_f32 v162, v161, v162, 0xbcdac9b8
	v_fmaak_f32 v162, v161, v162, 0x3de703be
	v_fmaak_f32 v162, v161, v162, 0xbec09330
	v_fmaak_f32 v161, v161, v162, 0x3e0375d0
	v_fma_f32 v165, |v160|, v161, |v160|
	v_fma_f32 v161, |v160|, s72, v9
	v_fma_f32 v161, |v160|, v161, s73
	v_fma_f32 v161, |v160|, v161, s74
	v_fma_f32 v161, |v160|, v161, s75
	v_fma_f32 v161, |v160|, v161, s76
	v_fma_f32 v161, |v160|, v161, s77
	v_fma_f32 v161, |v160|, v161, |v160|
	v_mul_f32_e32 v162, 0xbfb8aa3b, v161
	v_fma_f32 v163, v161, s78, -v162
	v_rndne_f32_e32 v164, v162
	v_fmac_f32_e32 v163, 0xb2a5705f, v161
	v_sub_f32_e32 v162, v162, v164
; DEV unsigned pack2(float a, float b) { float2v v = {a, b}; return __builtin_bit_cast(unsigned, __builtin_convertvector(v, bf16x2v)); }
; DEV float bflo(unsigned u) { return __uint_as_float(u << 16); }
; DEV float bfhi(unsigned u) { return __uint_as_float(u & 0xffff0000u); }
; DEV float gelu_exact(float v) { return 0.5f * v * (1.f + erff(v * 0.7071067811865476f)); }
; DEV void ph_scan2(const Params& p, int item) {
;     ...
; #pragma unroll 8
;   for (int t = 0; t < CHL; ++t) {
;     float4 a = *(const float4*)(p.a_arr + (row0 + t) * 1024 + ch);
;     float4 bb = *(const float4*)(p.b_arr + (row0 + t) * 1024 + ch);
;     u32x2 xg = *(const u32x2*)(p.z + (row0 + t) * ZLD + CXG + ch);
;     H[0] = a.x * H[0] + bb.x; H[1] = a.y * H[1] + bb.y; H[2] = a.z * H[2] + bb.z; H[3] = a.w * H[3] + bb.w;
;     u32x2 pk;
;     pk[0] = pack2(gelu_exact(bflo(xg[0])) * H[0], gelu_exact(bfhi(xg[0])) * H[1]);
;     pk[1] = pack2(gelu_exact(bflo(xg[1])) * H[2], gelu_exact(bfhi(xg[1])) * H[3]);
;     *(u32x2*)(p.orn + (row0 + t) * 1024 + ch) = pk;
;   }
	v_add_f32_e32 v162, v162, v163
	v_cvt_i32_f32_e32 v163, v164
	v_exp_f32_e32 v162, v162
	v_cmp_nlt_f32_e32 vcc, s79, v161
	v_ldexp_f32 v162, v162, v163
	s_nop 0
	v_cndmask_b32_e32 v162, 0, v162, vcc
	v_cmp_ngt_f32_e32 vcc, s80, v161
	s_nop 1
	v_cndmask_b32_e32 v161, v3, v162, vcc
	v_sub_f32_e32 v166, 1.0, v161
	v_cmp_lt_f32_e64 vcc, |v160|, 1.0
	s_nop 1
	v_cndmask_b32_e32 v165, v166, v165, vcc
	v_bfi_b32 v165, s81, v165, v160
	v_mul_f32_e32 v161, 0.5, v170
	v_add_f32_e32 v165, 1.0, v165
	v_mul_f32_e32 v161, v161, v165
	v_mul_f32_e32 v178, v161, v6
	v_mul_f32_e32 v160, 0x3f3504f3, v171
	v_mul_f32_e32 v161, v160, v160
	v_fmamk_f32 v162, v161, 0xba1345e1, v8
	v_fmaak_f32 v162, v161, v162, 0xbcdac9b8
	v_fmaak_f32 v162, v161, v162, 0x3de703be
	v_fmaak_f32 v162, v161, v162, 0xbec09330
	v_fmaak_f32 v161, v161, v162, 0x3e0375d0
	v_fma_f32 v165, |v160|, v161, |v160|
	v_fma_f32 v161, |v160|, s72, v9
	v_fma_f32 v161, |v160|, v161, s73
	v_fma_f32 v161, |v160|, v161, s74
	v_fma_f32 v161, |v160|, v161, s75
	v_fma_f32 v161, |v160|, v161, s76
	v_fma_f32 v161, |v160|, v161, s77
	v_fma_f32 v161, |v160|, v161, |v160|
	v_mul_f32_e32 v162, 0xbfb8aa3b, v161
	v_fma_f32 v163, v161, s78, -v162
	v_rndne_f32_e32 v164, v162
	v_fmac_f32_e32 v163, 0xb2a5705f, v161
	v_sub_f32_e32 v162, v162, v164
	v_add_f32_e32 v162, v162, v163
	v_cvt_i32_f32_e32 v163, v164
	v_exp_f32_e32 v162, v162
	v_cmp_nlt_f32_e32 vcc, s79, v161
	v_ldexp_f32 v162, v162, v163
	s_nop 0
	v_cndmask_b32_e32 v162, 0, v162, vcc
	v_cmp_ngt_f32_e32 vcc, s80, v161
	s_nop 1
	v_cndmask_b32_e32 v161, v3, v162, vcc
	v_sub_f32_e32 v166, 1.0, v161
	v_cmp_lt_f32_e64 vcc, |v160|, 1.0
	s_nop 1
	v_cndmask_b32_e32 v165, v166, v165, vcc
	v_bfi_b32 v165, s81, v165, v160
	v_mul_f32_e32 v161, 0.5, v171
	v_add_f32_e32 v165, 1.0, v165
	v_mul_f32_e32 v161, v161, v165
	v_mul_f32_e32 v179, v161, v7
	v_cvt_pk_bf16_f32 v180, v176, v177
	v_cvt_pk_bf16_f32 v181, v178, v179
	global_store_dwordx2 v2, v[180:181], s[34:35]
	s_add_u32 s34, s34, 0x800
	s_addc_u32 s35, s35, 0
	s_waitcnt vmcnt(13)
	v_fma_f32 v4, v120, v4, v124
	v_fma_f32 v5, v121, v5, v125
	v_fma_f32 v6, v122, v6, v126
	v_fma_f32 v7, v123, v7, v127
	v_lshlrev_b32_e32 v168, 16, v128
	v_and_b32_e32 v169, 0xffff0000, v128
	v_lshlrev_b32_e32 v170, 16, v129
	v_and_b32_e32 v171, 0xffff0000, v129
	v_mul_f32_e32 v160, 0x3f3504f3, v168
	v_mul_f32_e32 v161, v160, v160
	v_fmamk_f32 v162, v161, 0xba1345e1, v8
	v_fmaak_f32 v162, v161, v162, 0xbcdac9b8
	v_fmaak_f32 v162, v161, v162, 0x3de703be
	v_fmaak_f32 v162, v161, v162, 0xbec09330
	v_fmaak_f32 v161, v161, v162, 0x3e0375d0
	v_fma_f32 v165, |v160|, v161, |v160|
	v_fma_f32 v161, |v160|, s72, v9
	v_fma_f32 v161, |v160|, v161, s73
	v_fma_f32 v161, |v160|, v161, s74
	v_fma_f32 v161, |v160|, v161, s75
	v_fma_f32 v161, |v160|, v161, s76
	v_fma_f32 v161, |v160|, v161, s77
	v_fma_f32 v161, |v160|, v161, |v160|
	v_mul_f32_e32 v162, 0xbfb8aa3b, v161
	v_fma_f32 v163, v161, s78, -v162
	v_rndne_f32_e32 v164, v162
	v_fmac_f32_e32 v163, 0xb2a5705f, v161
	v_sub_f32_e32 v162, v162, v164
	v_add_f32_e32 v162, v162, v163
	v_cvt_i32_f32_e32 v163, v164
	v_exp_f32_e32 v162, v162
	v_cmp_nlt_f32_e32 vcc, s79, v161
	v_ldexp_f32 v162, v162, v163
	s_nop 0
	v_cndmask_b32_e32 v162, 0, v162, vcc
	v_cmp_ngt_f32_e32 vcc, s80, v161
	s_nop 1
	v_cndmask_b32_e32 v161, v3, v162, vcc
	v_sub_f32_e32 v166, 1.0, v161
	v_cmp_lt_f32_e64 vcc, |v160|, 1.0
	s_nop 1
	v_cndmask_b32_e32 v165, v166, v165, vcc
	v_bfi_b32 v165, s81, v165, v160
	v_mul_f32_e32 v161, 0.5, v168
	v_add_f32_e32 v165, 1.0, v165
	v_mul_f32_e32 v161, v161, v165
	v_mul_f32_e32 v176, v161, v4
	v_mul_f32_e32 v160, 0x3f3504f3, v169
	v_mul_f32_e32 v161, v160, v160
	v_fmamk_f32 v162, v161, 0xba1345e1, v8
	v_fmaak_f32 v162, v161, v162, 0xbcdac9b8
	v_fmaak_f32 v162, v161, v162, 0x3de703be
	v_fmaak_f32 v162, v161, v162, 0xbec09330
	v_fmaak_f32 v161, v161, v162, 0x3e0375d0
	v_fma_f32 v165, |v160|, v161, |v160|
	v_fma_f32 v161, |v160|, s72, v9
	v_fma_f32 v161, |v160|, v161, s73
	v_fma_f32 v161, |v160|, v161, s74
	v_fma_f32 v161, |v160|, v161, s75
	v_fma_f32 v161, |v160|, v161, s76
	v_fma_f32 v161, |v160|, v161, s77
	v_fma_f32 v161, |v160|, v161, |v160|
	v_mul_f32_e32 v162, 0xbfb8aa3b, v161
	v_fma_f32 v163, v161, s78, -v162
	v_rndne_f32_e32 v164, v162
	v_fmac_f32_e32 v163, 0xb2a5705f, v161
	v_sub_f32_e32 v162, v162, v164
	v_add_f32_e32 v162, v162, v163
	v_cvt_i32_f32_e32 v163, v164
	v_exp_f32_e32 v162, v162
	v_cmp_nlt_f32_e32 vcc, s79, v161
	v_ldexp_f32 v162, v162, v163
	s_nop 0
	v_cndmask_b32_e32 v162, 0, v162, vcc
	v_cmp_ngt_f32_e32 vcc, s80, v161
	s_nop 1
	v_cndmask_b32_e32 v161, v3, v162, vcc
	v_sub_f32_e32 v166, 1.0, v161
	v_cmp_lt_f32_e64 vcc, |v160|, 1.0
	s_nop 1
	v_cndmask_b32_e32 v165, v166, v165, vcc
	v_bfi_b32 v165, s81, v165, v160
	v_mul_f32_e32 v161, 0.5, v169
	v_add_f32_e32 v165, 1.0, v165
	v_mul_f32_e32 v161, v161, v165
	v_mul_f32_e32 v177, v161, v5
	v_mul_f32_e32 v160, 0x3f3504f3, v170
	v_mul_f32_e32 v161, v160, v160
	v_fmamk_f32 v162, v161, 0xba1345e1, v8
	v_fmaak_f32 v162, v161, v162, 0xbcdac9b8
	v_fmaak_f32 v162, v161, v162, 0x3de703be
	v_fmaak_f32 v162, v161, v162, 0xbec09330
	v_fmaak_f32 v161, v161, v162, 0x3e0375d0
	v_fma_f32 v165, |v160|, v161, |v160|
	v_fma_f32 v161, |v160|, s72, v9
	v_fma_f32 v161, |v160|, v161, s73
	v_fma_f32 v161, |v160|, v161, s74
	v_fma_f32 v161, |v160|, v161, s75
	v_fma_f32 v161, |v160|, v161, s76
	v_fma_f32 v161, |v160|, v161, s77
	v_fma_f32 v161, |v160|, v161, |v160|
	v_mul_f32_e32 v162, 0xbfb8aa3b, v161
	v_fma_f32 v163, v161, s78, -v162
	v_rndne_f32_e32 v164, v162
	v_fmac_f32_e32 v163, 0xb2a5705f, v161
	v_sub_f32_e32 v162, v162, v164
	v_add_f32_e32 v162, v162, v163
; DEV unsigned pack2(float a, float b) { float2v v = {a, b}; return __builtin_bit_cast(unsigned, __builtin_convertvector(v, bf16x2v)); }
; DEV float bflo(unsigned u) { return __uint_as_float(u << 16); }
; DEV float bfhi(unsigned u) { return __uint_as_float(u & 0xffff0000u); }
; DEV float gelu_exact(float v) { return 0.5f * v * (1.f + erff(v * 0.7071067811865476f)); }
; DEV void ph_scan2(const Params& p, int item) {
;     ...
; #pragma unroll 8
;   for (int t = 0; t < CHL; ++t) {
;     float4 a = *(const float4*)(p.a_arr + (row0 + t) * 1024 + ch);
;     float4 bb = *(const float4*)(p.b_arr + (row0 + t) * 1024 + ch);
;     u32x2 xg = *(const u32x2*)(p.z + (row0 + t) * ZLD + CXG + ch);
;     H[0] = a.x * H[0] + bb.x; H[1] = a.y * H[1] + bb.y; H[2] = a.z * H[2] + bb.z; H[3] = a.w * H[3] + bb.w;
;     u32x2 pk;
;     pk[0] = pack2(gelu_exact(bflo(xg[0])) * H[0], gelu_exact(bfhi(xg[0])) * H[1]);
;     pk[1] = pack2(gelu_exact(bflo(xg[1])) * H[2], gelu_exact(bfhi(xg[1])) * H[3]);
;     *(u32x2*)(p.orn + (row0 + t) * 1024 + ch) = pk;
;   }
	v_cvt_i32_f32_e32 v163, v164
	v_exp_f32_e32 v162, v162
	v_cmp_nlt_f32_e32 vcc, s79, v161
	v_ldexp_f32 v162, v162, v163
	s_nop 0
	v_cndmask_b32_e32 v162, 0, v162, vcc
	v_cmp_ngt_f32_e32 vcc, s80, v161
	s_nop 1
	v_cndmask_b32_e32 v161, v3, v162, vcc
	v_sub_f32_e32 v166, 1.0, v161
	v_cmp_lt_f32_e64 vcc, |v160|, 1.0
	s_nop 1
	v_cndmask_b32_e32 v165, v166, v165, vcc
	v_bfi_b32 v165, s81, v165, v160
	v_mul_f32_e32 v161, 0.5, v170
	v_add_f32_e32 v165, 1.0, v165
	v_mul_f32_e32 v161, v161, v165
	v_mul_f32_e32 v178, v161, v6
	v_mul_f32_e32 v160, 0x3f3504f3, v171
	v_mul_f32_e32 v161, v160, v160
	v_fmamk_f32 v162, v161, 0xba1345e1, v8
	v_fmaak_f32 v162, v161, v162, 0xbcdac9b8
	v_fmaak_f32 v162, v161, v162, 0x3de703be
	v_fmaak_f32 v162, v161, v162, 0xbec09330
	v_fmaak_f32 v161, v161, v162, 0x3e0375d0
	v_fma_f32 v165, |v160|, v161, |v160|
	v_fma_f32 v161, |v160|, s72, v9
	v_fma_f32 v161, |v160|, v161, s73
	v_fma_f32 v161, |v160|, v161, s74
	v_fma_f32 v161, |v160|, v161, s75
	v_fma_f32 v161, |v160|, v161, s76
	v_fma_f32 v161, |v160|, v161, s77
	v_fma_f32 v161, |v160|, v161, |v160|
	v_mul_f32_e32 v162, 0xbfb8aa3b, v161
	v_fma_f32 v163, v161, s78, -v162
	v_rndne_f32_e32 v164, v162
	v_fmac_f32_e32 v163, 0xb2a5705f, v161
	v_sub_f32_e32 v162, v162, v164
	v_add_f32_e32 v162, v162, v163
	v_cvt_i32_f32_e32 v163, v164
	v_exp_f32_e32 v162, v162
	v_cmp_nlt_f32_e32 vcc, s79, v161
	v_ldexp_f32 v162, v162, v163
	s_nop 0
	v_cndmask_b32_e32 v162, 0, v162, vcc
	v_cmp_ngt_f32_e32 vcc, s80, v161
	s_nop 1
	v_cndmask_b32_e32 v161, v3, v162, vcc
	v_sub_f32_e32 v166, 1.0, v161
	v_cmp_lt_f32_e64 vcc, |v160|, 1.0
	s_nop 1
	v_cndmask_b32_e32 v165, v166, v165, vcc
	v_bfi_b32 v165, s81, v165, v160
	v_mul_f32_e32 v161, 0.5, v171
	v_add_f32_e32 v165, 1.0, v165
	v_mul_f32_e32 v161, v161, v165
	v_mul_f32_e32 v179, v161, v7
	v_cvt_pk_bf16_f32 v180, v176, v177
	v_cvt_pk_bf16_f32 v181, v178, v179
	global_store_dwordx2 v2, v[180:181], s[34:35]
	s_add_u32 s34, s34, 0x800
	s_addc_u32 s35, s35, 0
	s_waitcnt vmcnt(11)
	v_fma_f32 v4, v130, v4, v134
	v_fma_f32 v5, v131, v5, v135
	v_fma_f32 v6, v132, v6, v136
	v_fma_f32 v7, v133, v7, v137
	v_lshlrev_b32_e32 v168, 16, v138
	v_and_b32_e32 v169, 0xffff0000, v138
	v_lshlrev_b32_e32 v170, 16, v139
	v_and_b32_e32 v171, 0xffff0000, v139
	v_mul_f32_e32 v160, 0x3f3504f3, v168
	v_mul_f32_e32 v161, v160, v160
	v_fmamk_f32 v162, v161, 0xba1345e1, v8
	v_fmaak_f32 v162, v161, v162, 0xbcdac9b8
	v_fmaak_f32 v162, v161, v162, 0x3de703be
	v_fmaak_f32 v162, v161, v162, 0xbec09330
	v_fmaak_f32 v161, v161, v162, 0x3e0375d0
	v_fma_f32 v165, |v160|, v161, |v160|
	v_fma_f32 v161, |v160|, s72, v9
	v_fma_f32 v161, |v160|, v161, s73
	v_fma_f32 v161, |v160|, v161, s74
	v_fma_f32 v161, |v160|, v161, s75
	v_fma_f32 v161, |v160|, v161, s76
	v_fma_f32 v161, |v160|, v161, s77
	v_fma_f32 v161, |v160|, v161, |v160|
	v_mul_f32_e32 v162, 0xbfb8aa3b, v161
	v_fma_f32 v163, v161, s78, -v162
	v_rndne_f32_e32 v164, v162
	v_fmac_f32_e32 v163, 0xb2a5705f, v161
	v_sub_f32_e32 v162, v162, v164
	v_add_f32_e32 v162, v162, v163
	v_cvt_i32_f32_e32 v163, v164
	v_exp_f32_e32 v162, v162
	v_cmp_nlt_f32_e32 vcc, s79, v161
	v_ldexp_f32 v162, v162, v163
	s_nop 0
	v_cndmask_b32_e32 v162, 0, v162, vcc
	v_cmp_ngt_f32_e32 vcc, s80, v161
	s_nop 1
	v_cndmask_b32_e32 v161, v3, v162, vcc
	v_sub_f32_e32 v166, 1.0, v161
	v_cmp_lt_f32_e64 vcc, |v160|, 1.0
	s_nop 1
	v_cndmask_b32_e32 v165, v166, v165, vcc
	v_bfi_b32 v165, s81, v165, v160
	v_mul_f32_e32 v161, 0.5, v168
	v_add_f32_e32 v165, 1.0, v165
	v_mul_f32_e32 v161, v161, v165
	v_mul_f32_e32 v176, v161, v4
	v_mul_f32_e32 v160, 0x3f3504f3, v169
	v_mul_f32_e32 v161, v160, v160
	v_fmamk_f32 v162, v161, 0xba1345e1, v8
	v_fmaak_f32 v162, v161, v162, 0xbcdac9b8
	v_fmaak_f32 v162, v161, v162, 0x3de703be
	v_fmaak_f32 v162, v161, v162, 0xbec09330
	v_fmaak_f32 v161, v161, v162, 0x3e0375d0
	v_fma_f32 v165, |v160|, v161, |v160|
	v_fma_f32 v161, |v160|, s72, v9
	v_fma_f32 v161, |v160|, v161, s73
	v_fma_f32 v161, |v160|, v161, s74
	v_fma_f32 v161, |v160|, v161, s75
	v_fma_f32 v161, |v160|, v161, s76
	v_fma_f32 v161, |v160|, v161, s77
	v_fma_f32 v161, |v160|, v161, |v160|
	v_mul_f32_e32 v162, 0xbfb8aa3b, v161
	v_fma_f32 v163, v161, s78, -v162
	v_rndne_f32_e32 v164, v162
	v_fmac_f32_e32 v163, 0xb2a5705f, v161
	v_sub_f32_e32 v162, v162, v164
	v_add_f32_e32 v162, v162, v163
	v_cvt_i32_f32_e32 v163, v164
	v_exp_f32_e32 v162, v162
	v_cmp_nlt_f32_e32 vcc, s79, v161
	v_ldexp_f32 v162, v162, v163
	s_nop 0
	v_cndmask_b32_e32 v162, 0, v162, vcc
	v_cmp_ngt_f32_e32 vcc, s80, v161
	s_nop 1
	v_cndmask_b32_e32 v161, v3, v162, vcc
	v_sub_f32_e32 v166, 1.0, v161
	v_cmp_lt_f32_e64 vcc, |v160|, 1.0
	s_nop 1
	v_cndmask_b32_e32 v165, v166, v165, vcc
	v_bfi_b32 v165, s81, v165, v160
	v_mul_f32_e32 v161, 0.5, v169
	v_add_f32_e32 v165, 1.0, v165
	v_mul_f32_e32 v161, v161, v165
	v_mul_f32_e32 v177, v161, v5
	v_mul_f32_e32 v160, 0x3f3504f3, v170
	v_mul_f32_e32 v161, v160, v160
	v_fmamk_f32 v162, v161, 0xba1345e1, v8
	v_fmaak_f32 v162, v161, v162, 0xbcdac9b8
	v_fmaak_f32 v162, v161, v162, 0x3de703be
	v_fmaak_f32 v162, v161, v162, 0xbec09330
	v_fmaak_f32 v161, v161, v162, 0x3e0375d0
	v_fma_f32 v165, |v160|, v161, |v160|
	v_fma_f32 v161, |v160|, s72, v9
	v_fma_f32 v161, |v160|, v161, s73
	v_fma_f32 v161, |v160|, v161, s74
	v_fma_f32 v161, |v160|, v161, s75
	v_fma_f32 v161, |v160|, v161, s76
	v_fma_f32 v161, |v160|, v161, s77
	v_fma_f32 v161, |v160|, v161, |v160|
	v_mul_f32_e32 v162, 0xbfb8aa3b, v161
	v_fma_f32 v163, v161, s78, -v162
	v_rndne_f32_e32 v164, v162
	v_fmac_f32_e32 v163, 0xb2a5705f, v161
	v_sub_f32_e32 v162, v162, v164
	v_add_f32_e32 v162, v162, v163
	v_cvt_i32_f32_e32 v163, v164
; DEV unsigned pack2(float a, float b) { float2v v = {a, b}; return __builtin_bit_cast(unsigned, __builtin_convertvector(v, bf16x2v)); }
; DEV float bflo(unsigned u) { return __uint_as_float(u << 16); }
; DEV float bfhi(unsigned u) { return __uint_as_float(u & 0xffff0000u); }
; DEV float gelu_exact(float v) { return 0.5f * v * (1.f + erff(v * 0.7071067811865476f)); }
; DEV void ph_scan2(const Params& p, int item) {
;     ...
;   for (int t = 0; t < CHL; ++t) {
;     float4 a = *(const float4*)(p.a_arr + (row0 + t) * 1024 + ch);
;     float4 bb = *(const float4*)(p.b_arr + (row0 + t) * 1024 + ch);
;     u32x2 xg = *(const u32x2*)(p.z + (row0 + t) * ZLD + CXG + ch);
;     H[0] = a.x * H[0] + bb.x; H[1] = a.y * H[1] + bb.y; H[2] = a.z * H[2] + bb.z; H[3] = a.w * H[3] + bb.w;
;     u32x2 pk;
;     pk[0] = pack2(gelu_exact(bflo(xg[0])) * H[0], gelu_exact(bfhi(xg[0])) * H[1]);
;     pk[1] = pack2(gelu_exact(bflo(xg[1])) * H[2], gelu_exact(bfhi(xg[1])) * H[3]);
;     *(u32x2*)(p.orn + (row0 + t) * 1024 + ch) = pk;
;   }
	v_exp_f32_e32 v162, v162
	v_cmp_nlt_f32_e32 vcc, s79, v161
	v_ldexp_f32 v162, v162, v163
	s_nop 0
	v_cndmask_b32_e32 v162, 0, v162, vcc
	v_cmp_ngt_f32_e32 vcc, s80, v161
	s_nop 1
	v_cndmask_b32_e32 v161, v3, v162, vcc
	v_sub_f32_e32 v166, 1.0, v161
	v_cmp_lt_f32_e64 vcc, |v160|, 1.0
	s_nop 1
	v_cndmask_b32_e32 v165, v166, v165, vcc
	v_bfi_b32 v165, s81, v165, v160
	v_mul_f32_e32 v161, 0.5, v170
	v_add_f32_e32 v165, 1.0, v165
	v_mul_f32_e32 v161, v161, v165
	v_mul_f32_e32 v178, v161, v6
	v_mul_f32_e32 v160, 0x3f3504f3, v171
	v_mul_f32_e32 v161, v160, v160
	v_fmamk_f32 v162, v161, 0xba1345e1, v8
	v_fmaak_f32 v162, v161, v162, 0xbcdac9b8
	v_fmaak_f32 v162, v161, v162, 0x3de703be
	v_fmaak_f32 v162, v161, v162, 0xbec09330
	v_fmaak_f32 v161, v161, v162, 0x3e0375d0
	v_fma_f32 v165, |v160|, v161, |v160|
	v_fma_f32 v161, |v160|, s72, v9
	v_fma_f32 v161, |v160|, v161, s73
	v_fma_f32 v161, |v160|, v161, s74
	v_fma_f32 v161, |v160|, v161, s75
	v_fma_f32 v161, |v160|, v161, s76
	v_fma_f32 v161, |v160|, v161, s77
	v_fma_f32 v161, |v160|, v161, |v160|
	v_mul_f32_e32 v162, 0xbfb8aa3b, v161
	v_fma_f32 v163, v161, s78, -v162
	v_rndne_f32_e32 v164, v162
	v_fmac_f32_e32 v163, 0xb2a5705f, v161
	v_sub_f32_e32 v162, v162, v164
	v_add_f32_e32 v162, v162, v163
	v_cvt_i32_f32_e32 v163, v164
	v_exp_f32_e32 v162, v162
	v_cmp_nlt_f32_e32 vcc, s79, v161
	v_ldexp_f32 v162, v162, v163
	s_nop 0
	v_cndmask_b32_e32 v162, 0, v162, vcc
	v_cmp_ngt_f32_e32 vcc, s80, v161
	s_nop 1
	v_cndmask_b32_e32 v161, v3, v162, vcc
	v_sub_f32_e32 v166, 1.0, v161
	v_cmp_lt_f32_e64 vcc, |v160|, 1.0
	s_nop 1
	v_cndmask_b32_e32 v165, v166, v165, vcc
	v_bfi_b32 v165, s81, v165, v160
	v_mul_f32_e32 v161, 0.5, v171
	v_add_f32_e32 v165, 1.0, v165
	v_mul_f32_e32 v161, v161, v165
	v_mul_f32_e32 v179, v161, v7
	v_cvt_pk_bf16_f32 v180, v176, v177
	v_cvt_pk_bf16_f32 v181, v178, v179
	global_store_dwordx2 v2, v[180:181], s[34:35]
	s_add_u32 s34, s34, 0x800
	s_addc_u32 s35, s35, 0
	s_waitcnt vmcnt(9)
	v_fma_f32 v4, v140, v4, v144
	v_fma_f32 v5, v141, v5, v145
	v_fma_f32 v6, v142, v6, v146
	v_fma_f32 v7, v143, v7, v147
	v_lshlrev_b32_e32 v168, 16, v148
	v_and_b32_e32 v169, 0xffff0000, v148
	v_lshlrev_b32_e32 v170, 16, v149
	v_and_b32_e32 v171, 0xffff0000, v149
	v_mul_f32_e32 v160, 0x3f3504f3, v168
	v_mul_f32_e32 v161, v160, v160
	v_fmamk_f32 v162, v161, 0xba1345e1, v8
	v_fmaak_f32 v162, v161, v162, 0xbcdac9b8
	v_fmaak_f32 v162, v161, v162, 0x3de703be
	v_fmaak_f32 v162, v161, v162, 0xbec09330
	v_fmaak_f32 v161, v161, v162, 0x3e0375d0
	v_fma_f32 v165, |v160|, v161, |v160|
	v_fma_f32 v161, |v160|, s72, v9
	v_fma_f32 v161, |v160|, v161, s73
	v_fma_f32 v161, |v160|, v161, s74
	v_fma_f32 v161, |v160|, v161, s75
	v_fma_f32 v161, |v160|, v161, s76
	v_fma_f32 v161, |v160|, v161, s77
	v_fma_f32 v161, |v160|, v161, |v160|
	v_mul_f32_e32 v162, 0xbfb8aa3b, v161
	v_fma_f32 v163, v161, s78, -v162
	v_rndne_f32_e32 v164, v162
	v_fmac_f32_e32 v163, 0xb2a5705f, v161
	v_sub_f32_e32 v162, v162, v164
	v_add_f32_e32 v162, v162, v163
	v_cvt_i32_f32_e32 v163, v164
	v_exp_f32_e32 v162, v162
	v_cmp_nlt_f32_e32 vcc, s79, v161
	v_ldexp_f32 v162, v162, v163
	s_nop 0
	v_cndmask_b32_e32 v162, 0, v162, vcc
	v_cmp_ngt_f32_e32 vcc, s80, v161
	s_nop 1
	v_cndmask_b32_e32 v161, v3, v162, vcc
	v_sub_f32_e32 v166, 1.0, v161
	v_cmp_lt_f32_e64 vcc, |v160|, 1.0
	s_nop 1
	v_cndmask_b32_e32 v165, v166, v165, vcc
	v_bfi_b32 v165, s81, v165, v160
	v_mul_f32_e32 v161, 0.5, v168
	v_add_f32_e32 v165, 1.0, v165
	v_mul_f32_e32 v161, v161, v165
	v_mul_f32_e32 v176, v161, v4
	v_mul_f32_e32 v160, 0x3f3504f3, v169
	v_mul_f32_e32 v161, v160, v160
	v_fmamk_f32 v162, v161, 0xba1345e1, v8
	v_fmaak_f32 v162, v161, v162, 0xbcdac9b8
	v_fmaak_f32 v162, v161, v162, 0x3de703be
	v_fmaak_f32 v162, v161, v162, 0xbec09330
	v_fmaak_f32 v161, v161, v162, 0x3e0375d0
	v_fma_f32 v165, |v160|, v161, |v160|
	v_fma_f32 v161, |v160|, s72, v9
	v_fma_f32 v161, |v160|, v161, s73
	v_fma_f32 v161, |v160|, v161, s74
	v_fma_f32 v161, |v160|, v161, s75
	v_fma_f32 v161, |v160|, v161, s76
	v_fma_f32 v161, |v160|, v161, s77
	v_fma_f32 v161, |v160|, v161, |v160|
	v_mul_f32_e32 v162, 0xbfb8aa3b, v161
	v_fma_f32 v163, v161, s78, -v162
	v_rndne_f32_e32 v164, v162
	v_fmac_f32_e32 v163, 0xb2a5705f, v161
	v_sub_f32_e32 v162, v162, v164
	v_add_f32_e32 v162, v162, v163
	v_cvt_i32_f32_e32 v163, v164
	v_exp_f32_e32 v162, v162
	v_cmp_nlt_f32_e32 vcc, s79, v161
	v_ldexp_f32 v162, v162, v163
	s_nop 0
	v_cndmask_b32_e32 v162, 0, v162, vcc
	v_cmp_ngt_f32_e32 vcc, s80, v161
	s_nop 1
	v_cndmask_b32_e32 v161, v3, v162, vcc
	v_sub_f32_e32 v166, 1.0, v161
	v_cmp_lt_f32_e64 vcc, |v160|, 1.0
	s_nop 1
	v_cndmask_b32_e32 v165, v166, v165, vcc
	v_bfi_b32 v165, s81, v165, v160
	v_mul_f32_e32 v161, 0.5, v169
	v_add_f32_e32 v165, 1.0, v165
	v_mul_f32_e32 v161, v161, v165
	v_mul_f32_e32 v177, v161, v5
	v_mul_f32_e32 v160, 0x3f3504f3, v170
	v_mul_f32_e32 v161, v160, v160
	v_fmamk_f32 v162, v161, 0xba1345e1, v8
	v_fmaak_f32 v162, v161, v162, 0xbcdac9b8
	v_fmaak_f32 v162, v161, v162, 0x3de703be
	v_fmaak_f32 v162, v161, v162, 0xbec09330
	v_fmaak_f32 v161, v161, v162, 0x3e0375d0
	v_fma_f32 v165, |v160|, v161, |v160|
	v_fma_f32 v161, |v160|, s72, v9
	v_fma_f32 v161, |v160|, v161, s73
	v_fma_f32 v161, |v160|, v161, s74
	v_fma_f32 v161, |v160|, v161, s75
	v_fma_f32 v161, |v160|, v161, s76
	v_fma_f32 v161, |v160|, v161, s77
	v_fma_f32 v161, |v160|, v161, |v160|
	v_mul_f32_e32 v162, 0xbfb8aa3b, v161
	v_fma_f32 v163, v161, s78, -v162
	v_rndne_f32_e32 v164, v162
	v_fmac_f32_e32 v163, 0xb2a5705f, v161
	v_sub_f32_e32 v162, v162, v164
	v_add_f32_e32 v162, v162, v163
	v_cvt_i32_f32_e32 v163, v164
	v_exp_f32_e32 v162, v162
; DEV unsigned pack2(float a, float b) { float2v v = {a, b}; return __builtin_bit_cast(unsigned, __builtin_convertvector(v, bf16x2v)); }
; DEV float bflo(unsigned u) { return __uint_as_float(u << 16); }
; DEV float bfhi(unsigned u) { return __uint_as_float(u & 0xffff0000u); }
; DEV float gelu_exact(float v) { return 0.5f * v * (1.f + erff(v * 0.7071067811865476f)); }
; DEV void ph_scan2(const Params& p, int item) {
;     ...
;     H[0] = a.x * H[0] + bb.x; H[1] = a.y * H[1] + bb.y; H[2] = a.z * H[2] + bb.z; H[3] = a.w * H[3] + bb.w;
;     u32x2 pk;
;     pk[0] = pack2(gelu_exact(bflo(xg[0])) * H[0], gelu_exact(bfhi(xg[0])) * H[1]);
;     pk[1] = pack2(gelu_exact(bflo(xg[1])) * H[2], gelu_exact(bfhi(xg[1])) * H[3]);
;     *(u32x2*)(p.orn + (row0 + t) * 1024 + ch) = pk;
	v_cmp_nlt_f32_e32 vcc, s79, v161
	v_ldexp_f32 v162, v162, v163
	s_nop 0
	v_cndmask_b32_e32 v162, 0, v162, vcc
	v_cmp_ngt_f32_e32 vcc, s80, v161
	s_nop 1
	v_cndmask_b32_e32 v161, v3, v162, vcc
	v_sub_f32_e32 v166, 1.0, v161
	v_cmp_lt_f32_e64 vcc, |v160|, 1.0
	s_nop 1
	v_cndmask_b32_e32 v165, v166, v165, vcc
	v_bfi_b32 v165, s81, v165, v160
	v_mul_f32_e32 v161, 0.5, v170
	v_add_f32_e32 v165, 1.0, v165
	v_mul_f32_e32 v161, v161, v165
	v_mul_f32_e32 v178, v161, v6
	v_mul_f32_e32 v160, 0x3f3504f3, v171
	v_mul_f32_e32 v161, v160, v160
	v_fmamk_f32 v162, v161, 0xba1345e1, v8
	v_fmaak_f32 v162, v161, v162, 0xbcdac9b8
	v_fmaak_f32 v162, v161, v162, 0x3de703be
	v_fmaak_f32 v162, v161, v162, 0xbec09330
	v_fmaak_f32 v161, v161, v162, 0x3e0375d0
	v_fma_f32 v165, |v160|, v161, |v160|
	v_fma_f32 v161, |v160|, s72, v9
	v_fma_f32 v161, |v160|, v161, s73
	v_fma_f32 v161, |v160|, v161, s74
	v_fma_f32 v161, |v160|, v161, s75
	v_fma_f32 v161, |v160|, v161, s76
	v_fma_f32 v161, |v160|, v161, s77
	v_fma_f32 v161, |v160|, v161, |v160|
	v_mul_f32_e32 v162, 0xbfb8aa3b, v161
	v_fma_f32 v163, v161, s78, -v162
	v_rndne_f32_e32 v164, v162
	v_fmac_f32_e32 v163, 0xb2a5705f, v161
	v_sub_f32_e32 v162, v162, v164
	v_add_f32_e32 v162, v162, v163
	v_cvt_i32_f32_e32 v163, v164
	v_exp_f32_e32 v162, v162
	v_cmp_nlt_f32_e32 vcc, s79, v161
	v_ldexp_f32 v162, v162, v163
	s_nop 0
	v_cndmask_b32_e32 v162, 0, v162, vcc
	v_cmp_ngt_f32_e32 vcc, s80, v161
	s_nop 1
	v_cndmask_b32_e32 v161, v3, v162, vcc
	v_sub_f32_e32 v166, 1.0, v161
	v_cmp_lt_f32_e64 vcc, |v160|, 1.0
	s_nop 1
	v_cndmask_b32_e32 v165, v166, v165, vcc
	v_bfi_b32 v165, s81, v165, v160
	v_mul_f32_e32 v161, 0.5, v171
	v_add_f32_e32 v165, 1.0, v165
	v_mul_f32_e32 v161, v161, v165
	v_mul_f32_e32 v179, v161, v7
	v_cvt_pk_bf16_f32 v180, v176, v177
	v_cvt_pk_bf16_f32 v181, v178, v179
	global_store_dwordx2 v2, v[180:181], s[34:35]
	s_add_u32 s34, s34, 0x800
	s_addc_u32 s35, s35, 0
	s_waitcnt vmcnt(7)
; DEV unsigned pack2(float a, float b) { float2v v = {a, b}; return __builtin_bit_cast(unsigned, __builtin_convertvector(v, bf16x2v)); }
; DEV float bflo(unsigned u) { return __uint_as_float(u << 16); }
; DEV float bfhi(unsigned u) { return __uint_as_float(u & 0xffff0000u); }
; DEV float gelu_exact(float v) { return 0.5f * v * (1.f + erff(v * 0.7071067811865476f)); }
; DEV void ph_scan2(const Params& p, int item) {
;     ...
; #pragma unroll 8
;   for (int t = 0; t < CHL; ++t) {
;     float4 a = *(const float4*)(p.a_arr + (row0 + t) * 1024 + ch);
;     float4 bb = *(const float4*)(p.b_arr + (row0 + t) * 1024 + ch);
;     u32x2 xg = *(const u32x2*)(p.z + (row0 + t) * ZLD + CXG + ch);
;     H[0] = a.x * H[0] + bb.x; H[1] = a.y * H[1] + bb.y; H[2] = a.z * H[2] + bb.z; H[3] = a.w * H[3] + bb.w;
;     u32x2 pk;
;     pk[0] = pack2(gelu_exact(bflo(xg[0])) * H[0], gelu_exact(bfhi(xg[0])) * H[1]);
;     pk[1] = pack2(gelu_exact(bflo(xg[1])) * H[2], gelu_exact(bfhi(xg[1])) * H[3]);
;     *(u32x2*)(p.orn + (row0 + t) * 1024 + ch) = pk;
;   }
; __global__ void __launch_bounds__(256, 2) fwd_megakernel(Params p) {
;     ...
;   for (int it = bid; it < B_ * NCH; it += nb) ph_scan2(p, it);
	v_fma_f32 v4, v150, v4, v154
	v_fma_f32 v5, v151, v5, v155
	v_fma_f32 v6, v152, v6, v156
	v_fma_f32 v7, v153, v7, v157
	v_lshlrev_b32_e32 v168, 16, v158
	v_and_b32_e32 v169, 0xffff0000, v158
	v_lshlrev_b32_e32 v170, 16, v159
	v_and_b32_e32 v171, 0xffff0000, v159
	v_mul_f32_e32 v160, 0x3f3504f3, v168
	v_mul_f32_e32 v161, v160, v160
	v_fmamk_f32 v162, v161, 0xba1345e1, v8
	v_fmaak_f32 v162, v161, v162, 0xbcdac9b8
	v_fmaak_f32 v162, v161, v162, 0x3de703be
	v_fmaak_f32 v162, v161, v162, 0xbec09330
	v_fmaak_f32 v161, v161, v162, 0x3e0375d0
	v_fma_f32 v165, |v160|, v161, |v160|
	v_fma_f32 v161, |v160|, s72, v9
	v_fma_f32 v161, |v160|, v161, s73
	v_fma_f32 v161, |v160|, v161, s74
	v_fma_f32 v161, |v160|, v161, s75
	v_fma_f32 v161, |v160|, v161, s76
	v_fma_f32 v161, |v160|, v161, s77
	v_fma_f32 v161, |v160|, v161, |v160|
	v_mul_f32_e32 v162, 0xbfb8aa3b, v161
	v_fma_f32 v163, v161, s78, -v162
	v_rndne_f32_e32 v164, v162
	v_fmac_f32_e32 v163, 0xb2a5705f, v161
	v_sub_f32_e32 v162, v162, v164
	v_add_f32_e32 v162, v162, v163
	v_cvt_i32_f32_e32 v163, v164
	v_exp_f32_e32 v162, v162
	v_cmp_nlt_f32_e32 vcc, s79, v161
	v_ldexp_f32 v162, v162, v163
	s_nop 0
	v_cndmask_b32_e32 v162, 0, v162, vcc
	v_cmp_ngt_f32_e32 vcc, s80, v161
	s_nop 1
	v_cndmask_b32_e32 v161, v3, v162, vcc
	v_sub_f32_e32 v166, 1.0, v161
	v_cmp_lt_f32_e64 vcc, |v160|, 1.0
	s_nop 1
	v_cndmask_b32_e32 v165, v166, v165, vcc
	v_bfi_b32 v165, s81, v165, v160
	v_mul_f32_e32 v161, 0.5, v168
	v_add_f32_e32 v165, 1.0, v165
	v_mul_f32_e32 v161, v161, v165
	v_mul_f32_e32 v176, v161, v4
	v_mul_f32_e32 v160, 0x3f3504f3, v169
	v_mul_f32_e32 v161, v160, v160
	v_fmamk_f32 v162, v161, 0xba1345e1, v8
	v_fmaak_f32 v162, v161, v162, 0xbcdac9b8
	v_fmaak_f32 v162, v161, v162, 0x3de703be
	v_fmaak_f32 v162, v161, v162, 0xbec09330
	v_fmaak_f32 v161, v161, v162, 0x3e0375d0
	v_fma_f32 v165, |v160|, v161, |v160|
	v_fma_f32 v161, |v160|, s72, v9
	v_fma_f32 v161, |v160|, v161, s73
	v_fma_f32 v161, |v160|, v161, s74
	v_fma_f32 v161, |v160|, v161, s75
	v_fma_f32 v161, |v160|, v161, s76
	v_fma_f32 v161, |v160|, v161, s77
	v_fma_f32 v161, |v160|, v161, |v160|
	v_mul_f32_e32 v162, 0xbfb8aa3b, v161
	v_fma_f32 v163, v161, s78, -v162
	v_rndne_f32_e32 v164, v162
	v_fmac_f32_e32 v163, 0xb2a5705f, v161
	v_sub_f32_e32 v162, v162, v164
	v_add_f32_e32 v162, v162, v163
	v_cvt_i32_f32_e32 v163, v164
	v_exp_f32_e32 v162, v162
	v_cmp_nlt_f32_e32 vcc, s79, v161
	v_ldexp_f32 v162, v162, v163
	s_nop 0
	v_cndmask_b32_e32 v162, 0, v162, vcc
	v_cmp_ngt_f32_e32 vcc, s80, v161
	s_nop 1
	v_cndmask_b32_e32 v161, v3, v162, vcc
	v_sub_f32_e32 v166, 1.0, v161
	v_cmp_lt_f32_e64 vcc, |v160|, 1.0
	s_nop 1
	v_cndmask_b32_e32 v165, v166, v165, vcc
	v_bfi_b32 v165, s81, v165, v160
	v_mul_f32_e32 v161, 0.5, v169
	v_add_f32_e32 v165, 1.0, v165
	v_mul_f32_e32 v161, v161, v165
	v_mul_f32_e32 v177, v161, v5
	v_mul_f32_e32 v160, 0x3f3504f3, v170
	v_mul_f32_e32 v161, v160, v160
	v_fmamk_f32 v162, v161, 0xba1345e1, v8
	v_fmaak_f32 v162, v161, v162, 0xbcdac9b8
	v_fmaak_f32 v162, v161, v162, 0x3de703be
	v_fmaak_f32 v162, v161, v162, 0xbec09330
	v_fmaak_f32 v161, v161, v162, 0x3e0375d0
	v_fma_f32 v165, |v160|, v161, |v160|
	v_fma_f32 v161, |v160|, s72, v9
	v_fma_f32 v161, |v160|, v161, s73
	v_fma_f32 v161, |v160|, v161, s74
	v_fma_f32 v161, |v160|, v161, s75
	v_fma_f32 v161, |v160|, v161, s76
	v_fma_f32 v161, |v160|, v161, s77
	v_fma_f32 v161, |v160|, v161, |v160|
	v_mul_f32_e32 v162, 0xbfb8aa3b, v161
	v_fma_f32 v163, v161, s78, -v162
	v_rndne_f32_e32 v164, v162
	v_fmac_f32_e32 v163, 0xb2a5705f, v161
	v_sub_f32_e32 v162, v162, v164
	v_add_f32_e32 v162, v162, v163
	v_cvt_i32_f32_e32 v163, v164
	v_exp_f32_e32 v162, v162
	v_cmp_nlt_f32_e32 vcc, s79, v161
	v_ldexp_f32 v162, v162, v163
	s_nop 0
	v_cndmask_b32_e32 v162, 0, v162, vcc
	v_cmp_ngt_f32_e32 vcc, s80, v161
	s_nop 1
	v_cndmask_b32_e32 v161, v3, v162, vcc
	v_sub_f32_e32 v166, 1.0, v161
	v_cmp_lt_f32_e64 vcc, |v160|, 1.0
	s_nop 1
	v_cndmask_b32_e32 v165, v166, v165, vcc
	v_bfi_b32 v165, s81, v165, v160
	v_mul_f32_e32 v161, 0.5, v170
	v_add_f32_e32 v165, 1.0, v165
	v_mul_f32_e32 v161, v161, v165
	v_mul_f32_e32 v178, v161, v6
	v_mul_f32_e32 v160, 0x3f3504f3, v171
	v_mul_f32_e32 v161, v160, v160
	v_fmamk_f32 v162, v161, 0xba1345e1, v8
	v_fmaak_f32 v162, v161, v162, 0xbcdac9b8
	v_fmaak_f32 v162, v161, v162, 0x3de703be
	v_fmaak_f32 v162, v161, v162, 0xbec09330
	v_fmaak_f32 v161, v161, v162, 0x3e0375d0
	v_fma_f32 v165, |v160|, v161, |v160|
	v_fma_f32 v161, |v160|, s72, v9
	v_fma_f32 v161, |v160|, v161, s73
	v_fma_f32 v161, |v160|, v161, s74
	v_fma_f32 v161, |v160|, v161, s75
	v_fma_f32 v161, |v160|, v161, s76
	v_fma_f32 v161, |v160|, v161, s77
	v_fma_f32 v161, |v160|, v161, |v160|
	v_mul_f32_e32 v162, 0xbfb8aa3b, v161
	v_fma_f32 v163, v161, s78, -v162
	v_rndne_f32_e32 v164, v162
	v_fmac_f32_e32 v163, 0xb2a5705f, v161
	v_sub_f32_e32 v162, v162, v164
	v_add_f32_e32 v162, v162, v163
	v_cvt_i32_f32_e32 v163, v164
	v_exp_f32_e32 v162, v162
	v_cmp_nlt_f32_e32 vcc, s79, v161
	v_ldexp_f32 v162, v162, v163
	s_nop 0
	v_cndmask_b32_e32 v162, 0, v162, vcc
	v_cmp_ngt_f32_e32 vcc, s80, v161
	s_nop 1
	v_cndmask_b32_e32 v161, v3, v162, vcc
	v_sub_f32_e32 v166, 1.0, v161
	v_cmp_lt_f32_e64 vcc, |v160|, 1.0
	s_nop 1
	v_cndmask_b32_e32 v165, v166, v165, vcc
	v_bfi_b32 v165, s81, v165, v160
	v_mul_f32_e32 v161, 0.5, v171
	v_add_f32_e32 v165, 1.0, v165
	v_mul_f32_e32 v161, v161, v165
	v_mul_f32_e32 v179, v161, v7
	v_cvt_pk_bf16_f32 v180, v176, v177
	v_cvt_pk_bf16_f32 v181, v178, v179
	global_store_dwordx2 v2, v[180:181], s[34:35]
	s_add_u32 s34, s34, 0x800
	s_addc_u32 s35, s35, 0
	s_add_u32 s41, s41, 1
	s_cmp_lt_u32 s41, 4
	s_cbranch_scc1 .Lsc_main
	s_add_i32 s50, s50, s92
	s_cmpk_lt_i32 s50, 0x200
	s_cbranch_scc1 .Lsc_item

; DEV int ltid() { int t = threadIdx.x; asm volatile("" : "+v"(t)); return t; }
; __global__ void __launch_bounds__(256, 2) fwd_megakernel(Params p) {
;     ...
;                 const int t2 = ltid(), c4 = t2 & 31, r0 = t2 >> 5;
;                 const float4 g = *(const float4*)(gt1 + c4 * 4);
; #pragma unroll 4
;                 for (int ps = 0; ps < 16; ++ps) {
;                   const int r = ps * 8 + r0;
;                   const float4 sv = *(const float4*)(smf + r * 132 + c4 * 4);
;                   float4 xv = *(const float4*)(xin + (size_t)r * 2048 + c4 * 4);
;                   xv.x += g.x * sv.x; xv.y += g.y * sv.y; xv.z += g.z * sv.z; xv.w += g.w * sv.w;
;                   *(float4*)(ot + (size_t)r * 2048 + c4 * 4) = xv;
;                 }
.LBB0_1252:
	s_mov_b64 s[10:11], 0x0
	v_lshl_add_u64 v[252:253], v[138:139], 0, s[10:11]
	global_load_dwordx4 v[188:191], v[252:253], off
	s_mov_b64 s[10:11], 0x10000
	v_lshl_add_u64 v[252:253], v[138:139], 0, s[10:11]
	global_load_dwordx4 v[192:195], v[252:253], off
	s_mov_b64 s[10:11], 0x20000
	v_lshl_add_u64 v[252:253], v[138:139], 0, s[10:11]
	global_load_dwordx4 v[196:199], v[252:253], off
	s_mov_b64 s[10:11], 0x30000
	v_lshl_add_u64 v[252:253], v[138:139], 0, s[10:11]
	global_load_dwordx4 v[200:203], v[252:253], off
	s_mov_b64 s[10:11], 0x40000
	v_lshl_add_u64 v[252:253], v[138:139], 0, s[10:11]
	global_load_dwordx4 v[204:207], v[252:253], off
	s_mov_b64 s[10:11], 0x50000
	v_lshl_add_u64 v[252:253], v[138:139], 0, s[10:11]
	global_load_dwordx4 v[208:211], v[252:253], off
	s_mov_b64 s[10:11], 0x60000
	v_lshl_add_u64 v[252:253], v[138:139], 0, s[10:11]
	global_load_dwordx4 v[212:215], v[252:253], off
	s_mov_b64 s[10:11], 0x70000
	v_lshl_add_u64 v[252:253], v[138:139], 0, s[10:11]
	global_load_dwordx4 v[216:219], v[252:253], off
	ds_read_b128 v[220:223], v140
	ds_read_b128 v[224:227], v140 offset:4224
	s_waitcnt vmcnt(7) lgkmcnt(1)
	v_pk_fma_f32 v[188:189], v[130:131], v[220:221], v[188:189]
	v_pk_fma_f32 v[190:191], v[132:133], v[222:223], v[190:191]
	s_mov_b64 s[10:11], 0x0
	v_lshl_add_u64 v[252:253], v[136:137], 0, s[10:11]
	global_store_dwordx4 v[252:253], v[188:191], off
	ds_read_b128 v[220:223], v140 offset:8448
	s_waitcnt vmcnt(7) lgkmcnt(1)
	v_pk_fma_f32 v[192:193], v[130:131], v[224:225], v[192:193]
	v_pk_fma_f32 v[194:195], v[132:133], v[226:227], v[194:195]
	s_mov_b64 s[10:11], 0x10000
	v_lshl_add_u64 v[252:253], v[136:137], 0, s[10:11]
	global_store_dwordx4 v[252:253], v[192:195], off
	ds_read_b128 v[224:227], v140 offset:12672
	s_waitcnt vmcnt(7) lgkmcnt(1)
	v_pk_fma_f32 v[196:197], v[130:131], v[220:221], v[196:197]
	v_pk_fma_f32 v[198:199], v[132:133], v[222:223], v[198:199]
	s_mov_b64 s[10:11], 0x20000
	v_lshl_add_u64 v[252:253], v[136:137], 0, s[10:11]
	global_store_dwordx4 v[252:253], v[196:199], off
	ds_read_b128 v[220:223], v140 offset:16896
	s_waitcnt vmcnt(7) lgkmcnt(1)
	v_pk_fma_f32 v[200:201], v[130:131], v[224:225], v[200:201]
	v_pk_fma_f32 v[202:203], v[132:133], v[226:227], v[202:203]
	s_mov_b64 s[10:11], 0x30000
	v_lshl_add_u64 v[252:253], v[136:137], 0, s[10:11]
	global_store_dwordx4 v[252:253], v[200:203], off
	ds_read_b128 v[224:227], v140 offset:21120
	s_waitcnt vmcnt(7) lgkmcnt(1)
	v_pk_fma_f32 v[204:205], v[130:131], v[220:221], v[204:205]
	v_pk_fma_f32 v[206:207], v[132:133], v[222:223], v[206:207]
	s_mov_b64 s[10:11], 0x40000
	v_lshl_add_u64 v[252:253], v[136:137], 0, s[10:11]
	global_store_dwordx4 v[252:253], v[204:207], off
	ds_read_b128 v[220:223], v140 offset:25344
	s_waitcnt vmcnt(7) lgkmcnt(1)
	v_pk_fma_f32 v[208:209], v[130:131], v[224:225], v[208:209]
	v_pk_fma_f32 v[210:211], v[132:133], v[226:227], v[210:211]
	s_mov_b64 s[10:11], 0x50000
	v_lshl_add_u64 v[252:253], v[136:137], 0, s[10:11]
	global_store_dwordx4 v[252:253], v[208:211], off
	ds_read_b128 v[224:227], v140 offset:29568
	s_waitcnt vmcnt(7) lgkmcnt(1)
	v_pk_fma_f32 v[212:213], v[130:131], v[220:221], v[212:213]
	v_pk_fma_f32 v[214:215], v[132:133], v[222:223], v[214:215]
	s_mov_b64 s[10:11], 0x60000
	v_lshl_add_u64 v[252:253], v[136:137], 0, s[10:11]
	global_store_dwordx4 v[252:253], v[212:215], off
	s_waitcnt vmcnt(7) lgkmcnt(0)
	v_pk_fma_f32 v[216:217], v[130:131], v[224:225], v[216:217]
	v_pk_fma_f32 v[218:219], v[132:133], v[226:227], v[218:219]
	s_mov_b64 s[10:11], 0x70000
	v_lshl_add_u64 v[252:253], v[136:137], 0, s[10:11]
	global_store_dwordx4 v[252:253], v[216:219], off
	s_mov_b64 s[10:11], 0x80000
	v_lshl_add_u64 v[252:253], v[138:139], 0, s[10:11]
	global_load_dwordx4 v[188:191], v[252:253], off
	s_mov_b64 s[10:11], 0x90000
	v_lshl_add_u64 v[252:253], v[138:139], 0, s[10:11]
	global_load_dwordx4 v[192:195], v[252:253], off
	s_mov_b64 s[10:11], 0xa0000
	v_lshl_add_u64 v[252:253], v[138:139], 0, s[10:11]
	global_load_dwordx4 v[196:199], v[252:253], off
	s_mov_b64 s[10:11], 0xb0000
	v_lshl_add_u64 v[252:253], v[138:139], 0, s[10:11]
	global_load_dwordx4 v[200:203], v[252:253], off
	s_mov_b64 s[10:11], 0xc0000
	v_lshl_add_u64 v[252:253], v[138:139], 0, s[10:11]
	global_load_dwordx4 v[204:207], v[252:253], off
	s_mov_b64 s[10:11], 0xd0000
	v_lshl_add_u64 v[252:253], v[138:139], 0, s[10:11]
	global_load_dwordx4 v[208:211], v[252:253], off
	s_mov_b64 s[10:11], 0xe0000
	v_lshl_add_u64 v[252:253], v[138:139], 0, s[10:11]
	global_load_dwordx4 v[212:215], v[252:253], off
	s_mov_b64 s[10:11], 0xf0000
	v_lshl_add_u64 v[252:253], v[138:139], 0, s[10:11]
	global_load_dwordx4 v[216:219], v[252:253], off
	ds_read_b128 v[220:223], v140 offset:33792
	ds_read_b128 v[224:227], v140 offset:38016
	s_waitcnt vmcnt(7) lgkmcnt(1)
	v_pk_fma_f32 v[188:189], v[130:131], v[220:221], v[188:189]
	v_pk_fma_f32 v[190:191], v[132:133], v[222:223], v[190:191]
	s_mov_b64 s[10:11], 0x80000
	v_lshl_add_u64 v[252:253], v[136:137], 0, s[10:11]
	global_store_dwordx4 v[252:253], v[188:191], off
	ds_read_b128 v[220:223], v140 offset:42240
	s_waitcnt vmcnt(7) lgkmcnt(1)
	v_pk_fma_f32 v[192:193], v[130:131], v[224:225], v[192:193]
	v_pk_fma_f32 v[194:195], v[132:133], v[226:227], v[194:195]
	s_mov_b64 s[10:11], 0x90000
	v_lshl_add_u64 v[252:253], v[136:137], 0, s[10:11]
	global_store_dwordx4 v[252:253], v[192:195], off
	ds_read_b128 v[224:227], v140 offset:46464
	s_waitcnt vmcnt(7) lgkmcnt(1)
	v_pk_fma_f32 v[196:197], v[130:131], v[220:221], v[196:197]
	v_pk_fma_f32 v[198:199], v[132:133], v[222:223], v[198:199]
	s_mov_b64 s[10:11], 0xa0000
	v_lshl_add_u64 v[252:253], v[136:137], 0, s[10:11]
	global_store_dwordx4 v[252:253], v[196:199], off
	ds_read_b128 v[220:223], v140 offset:50688
	s_waitcnt vmcnt(7) lgkmcnt(1)
; template <class AF, class EPI>
; DEV void gemm_tile256(AF aptr, const u16* Bt, int ldb, int K, EPI epi, char* smem) {
;     ...
;         if (wr == h) {
; #pragma unroll
;           for (int m = 0; m < 8; ++m)
; #pragma unroll
;             for (int n = 0; n < 4; ++n)
; #pragma unroll
;               for (int j = 0; j < 4; ++j) smf_[(m * 16 + fq2 * 4 + j) * STR + wc * 64 + n * 16 + fr2] = acc[m][n][j];
; __global__ void __launch_bounds__(256, 2) fwd_megakernel(Params p) {
;     ...
;                 for (int ps = 0; ps < 16; ++ps) {
;                   const int r = ps * 8 + r0;
;                   const float4 sv = *(const float4*)(smf + r * 132 + c4 * 4);
;                   float4 xv = *(const float4*)(xin + (size_t)r * 2048 + c4 * 4);
;                   xv.x += g.x * sv.x; xv.y += g.y * sv.y; xv.z += g.z * sv.z; xv.w += g.w * sv.w;
;                   *(float4*)(ot + (size_t)r * 2048 + c4 * 4) = xv;
;                 }
	v_pk_fma_f32 v[200:201], v[130:131], v[224:225], v[200:201]
	v_pk_fma_f32 v[202:203], v[132:133], v[226:227], v[202:203]
	s_mov_b64 s[10:11], 0xb0000
	v_lshl_add_u64 v[252:253], v[136:137], 0, s[10:11]
	global_store_dwordx4 v[252:253], v[200:203], off
	ds_read_b128 v[224:227], v140 offset:54912
	s_waitcnt vmcnt(7) lgkmcnt(1)
	v_pk_fma_f32 v[204:205], v[130:131], v[220:221], v[204:205]
	v_pk_fma_f32 v[206:207], v[132:133], v[222:223], v[206:207]
	s_mov_b64 s[10:11], 0xc0000
	v_lshl_add_u64 v[252:253], v[136:137], 0, s[10:11]
	global_store_dwordx4 v[252:253], v[204:207], off
	ds_read_b128 v[220:223], v140 offset:59136
	s_waitcnt vmcnt(7) lgkmcnt(1)
	v_pk_fma_f32 v[208:209], v[130:131], v[224:225], v[208:209]
	v_pk_fma_f32 v[210:211], v[132:133], v[226:227], v[210:211]
	s_mov_b64 s[10:11], 0xd0000
	v_lshl_add_u64 v[252:253], v[136:137], 0, s[10:11]
	global_store_dwordx4 v[252:253], v[208:211], off
	ds_read_b128 v[224:227], v140 offset:63360
	s_waitcnt vmcnt(7) lgkmcnt(1)
	v_pk_fma_f32 v[212:213], v[130:131], v[220:221], v[212:213]
	v_pk_fma_f32 v[214:215], v[132:133], v[222:223], v[214:215]
	s_mov_b64 s[10:11], 0xe0000
	v_lshl_add_u64 v[252:253], v[136:137], 0, s[10:11]
	global_store_dwordx4 v[252:253], v[212:215], off
	s_waitcnt vmcnt(7) lgkmcnt(0)
	v_pk_fma_f32 v[216:217], v[130:131], v[224:225], v[216:217]
	v_pk_fma_f32 v[218:219], v[132:133], v[226:227], v[218:219]
	s_mov_b64 s[10:11], 0xf0000
	v_lshl_add_u64 v[252:253], v[136:137], 0, s[10:11]
	global_store_dwordx4 v[252:253], v[216:219], off
	v_cmp_eq_u32_e32 vcc, 1, v1
	s_barrier
	s_and_saveexec_b64 s[10:11], vcc
	s_cbranch_execz .LBB0_1255
	ds_write2_b32 v187, v127, v128 offset0:4 offset1:136
	ds_write_b32 v177, v129 offset:1584
	ds_write2_b32 v177, v126, v122 offset1:16
	ds_write_b32 v178, v123 offset:64
	ds_write_b32 v179, v124 offset:64
	ds_write_b32 v180, v125 offset:64
	ds_write_b32 v177, v118 offset:128
	ds_write_b32 v178, v119 offset:128
	ds_write_b32 v179, v120 offset:128
	ds_write_b32 v180, v121 offset:128
	ds_write_b32 v177, v114 offset:192
	ds_write_b32 v178, v115 offset:192
	ds_write_b32 v179, v116 offset:192
	ds_write_b32 v180, v117 offset:192
	ds_write2_b32 v185, v110, v111 offset0:64 offset1:196
	ds_write2_b32 v186, v112, v113 offset0:72 offset1:204
	ds_write_b32 v171, v106 offset:64
	ds_write_b32 v172, v107 offset:64
	ds_write_b32 v173, v108 offset:64
	ds_write_b32 v174, v109 offset:64
	ds_write_b32 v171, v102 offset:128
	ds_write_b32 v172, v103 offset:128
	ds_write_b32 v173, v104 offset:128
	ds_write_b32 v174, v105 offset:128
	ds_write_b32 v171, v98 offset:192
	ds_write_b32 v172, v99 offset:192
	ds_write_b32 v173, v100 offset:192
	ds_write_b32 v174, v101 offset:192
	ds_write2_b32 v183, v94, v95 offset1:132
	ds_write2_b32 v184, v96, v97 offset0:8 offset1:140
	ds_write_b32 v165, v42 offset:64
	ds_write_b32 v166, v43 offset:64
	ds_write_b32 v167, v44 offset:64
	ds_write_b32 v168, v45 offset:64
	ds_write_b32 v165, v38 offset:128
	ds_write_b32 v166, v39 offset:128
	ds_write_b32 v167, v40 offset:128
	ds_write_b32 v168, v41 offset:128
	ds_write_b32 v165, v34 offset:192
	ds_write_b32 v166, v35 offset:192
	ds_write_b32 v167, v36 offset:192
	ds_write_b32 v168, v37 offset:192
	ds_write2_b32 v181, v30, v31 offset0:64 offset1:196
	ds_write2_b32 v182, v32, v33 offset0:72 offset1:204
	ds_write_b32 v161, v26 offset:64
	ds_write_b32 v162, v27 offset:64
	ds_write_b32 v163, v28 offset:64
	ds_write_b32 v164, v29 offset:64
	ds_write_b32 v161, v22 offset:128
	ds_write_b32 v162, v23 offset:128
	ds_write_b32 v163, v24 offset:128
	ds_write_b32 v164, v25 offset:128
	ds_write_b32 v161, v18 offset:192
	ds_write_b32 v162, v19 offset:192
	ds_write_b32 v163, v20 offset:192
	ds_write_b32 v164, v21 offset:192
	ds_write2_b32 v175, v14, v15 offset1:132
	ds_write2_b32 v176, v16, v17 offset0:8 offset1:140
	ds_write_b32 v155, v10 offset:64
	ds_write_b32 v156, v11 offset:64
	ds_write_b32 v157, v12 offset:64
	ds_write_b32 v158, v13 offset:64
	ds_write_b32 v155, v6 offset:128
	ds_write_b32 v156, v7 offset:128
	ds_write_b32 v157, v8 offset:128
	ds_write_b32 v158, v9 offset:128
	ds_write_b32 v155, v2 offset:192
	ds_write_b32 v156, v3 offset:192
	ds_write_b32 v157, v4 offset:192
	ds_write_b32 v158, v5 offset:192
	ds_write2_b32 v169, v46, v47 offset0:64 offset1:196
	ds_write2_b32 v170, v48, v49 offset0:72 offset1:204
	ds_write_b32 v149, v50 offset:64
	ds_write_b32 v150, v51 offset:64
	ds_write_b32 v151, v52 offset:64
	ds_write_b32 v152, v53 offset:64
	ds_write_b32 v149, v54 offset:128
	ds_write_b32 v150, v55 offset:128
	ds_write_b32 v151, v56 offset:128
	ds_write_b32 v152, v57 offset:128
	ds_write_b32 v149, v58 offset:192
	ds_write_b32 v150, v59 offset:192
	ds_write_b32 v151, v60 offset:192
	ds_write_b32 v152, v61 offset:192
	ds_write2_b32 v159, v62, v63 offset1:132
	ds_write2_b32 v160, v64, v65 offset0:8 offset1:140
	ds_write_b32 v145, v66 offset:64
	ds_write_b32 v146, v67 offset:64
	ds_write_b32 v147, v68 offset:64
	ds_write_b32 v148, v69 offset:64
	ds_write_b32 v145, v70 offset:128
	ds_write_b32 v146, v71 offset:128
	ds_write_b32 v147, v72 offset:128
	ds_write_b32 v148, v73 offset:128
	ds_write_b32 v145, v74 offset:192
	ds_write_b32 v146, v75 offset:192
	ds_write_b32 v147, v76 offset:192
	ds_write_b32 v148, v77 offset:192
	ds_write2_b32 v153, v78, v79 offset0:64 offset1:196
	ds_write2_b32 v154, v80, v81 offset0:72 offset1:204
	ds_write_b32 v134, v82 offset:64
	ds_write_b32 v142, v83 offset:64
	ds_write_b32 v143, v84 offset:64
	ds_write_b32 v144, v85 offset:64
	ds_write_b32 v134, v86 offset:128
	ds_write_b32 v142, v87 offset:128
	ds_write_b32 v143, v88 offset:128
	ds_write_b32 v144, v89 offset:128
	ds_write_b32 v134, v90 offset:192
	ds_write_b32 v142, v91 offset:192
	ds_write_b32 v143, v92 offset:192
	ds_write_b32 v144, v93 offset:192

; DEV int ltid() { int t = threadIdx.x; asm volatile("" : "+v"(t)); return t; }
; __global__ void __launch_bounds__(256, 2) fwd_megakernel(Params p) {
;     ...
;                 const float* xin = p.x + (size_t)(pm * 2 + h) * 128 * 2048 + pn * 128;
;                 float* ot = p.out + (size_t)(pm * 2 + h) * 128 * 2048 + pn * 128;
;                 stager(smf, 132);
;                 __syncthreads();
;                 const int t2 = ltid(), c4 = t2 & 31, r0 = t2 >> 5;
;                 const float4 g = *(const float4*)(gt1 + c4 * 4);
; #pragma unroll 4
;                 for (int ps = 0; ps < 16; ++ps) {
;                   const int r = ps * 8 + r0;
;                   const float4 sv = *(const float4*)(smf + r * 132 + c4 * 4);
;                   float4 xv = *(const float4*)(xin + (size_t)r * 2048 + c4 * 4);
;                   xv.x += g.x * sv.x; xv.y += g.y * sv.y; xv.z += g.z * sv.z; xv.w += g.w * sv.w;
;                   *(float4*)(ot + (size_t)r * 2048 + c4 * 4) = xv;
;                 }
.LBB0_1256:
	s_mov_b64 s[6:7], 0x100000
	v_lshl_add_u64 v[252:253], v[8:9], 0, s[6:7]
	global_load_dwordx4 v[188:191], v[252:253], off
	s_mov_b64 s[6:7], 0x110000
	v_lshl_add_u64 v[252:253], v[8:9], 0, s[6:7]
	global_load_dwordx4 v[192:195], v[252:253], off
	s_mov_b64 s[6:7], 0x120000
	v_lshl_add_u64 v[252:253], v[8:9], 0, s[6:7]
	global_load_dwordx4 v[196:199], v[252:253], off
	s_mov_b64 s[6:7], 0x130000
	v_lshl_add_u64 v[252:253], v[8:9], 0, s[6:7]
	global_load_dwordx4 v[200:203], v[252:253], off
	s_mov_b64 s[6:7], 0x140000
	v_lshl_add_u64 v[252:253], v[8:9], 0, s[6:7]
	global_load_dwordx4 v[204:207], v[252:253], off
	s_mov_b64 s[6:7], 0x150000
	v_lshl_add_u64 v[252:253], v[8:9], 0, s[6:7]
	global_load_dwordx4 v[208:211], v[252:253], off
	s_mov_b64 s[6:7], 0x160000
	v_lshl_add_u64 v[252:253], v[8:9], 0, s[6:7]
	global_load_dwordx4 v[212:215], v[252:253], off
	s_mov_b64 s[6:7], 0x170000
	v_lshl_add_u64 v[252:253], v[8:9], 0, s[6:7]
	global_load_dwordx4 v[216:219], v[252:253], off
	ds_read_b128 v[220:223], v10
	ds_read_b128 v[224:227], v10 offset:4224
	s_waitcnt vmcnt(7) lgkmcnt(1)
	v_pk_fma_f32 v[188:189], v[2:3], v[220:221], v[188:189]
	v_pk_fma_f32 v[190:191], v[4:5], v[222:223], v[190:191]
	s_mov_b64 s[6:7], 0x100000
	v_lshl_add_u64 v[252:253], v[6:7], 0, s[6:7]
	global_store_dwordx4 v[252:253], v[188:191], off
	ds_read_b128 v[220:223], v10 offset:8448
	s_waitcnt vmcnt(7) lgkmcnt(1)
	v_pk_fma_f32 v[192:193], v[2:3], v[224:225], v[192:193]
	v_pk_fma_f32 v[194:195], v[4:5], v[226:227], v[194:195]
	s_mov_b64 s[6:7], 0x110000
	v_lshl_add_u64 v[252:253], v[6:7], 0, s[6:7]
	global_store_dwordx4 v[252:253], v[192:195], off
	ds_read_b128 v[224:227], v10 offset:12672
	s_waitcnt vmcnt(7) lgkmcnt(1)
	v_pk_fma_f32 v[196:197], v[2:3], v[220:221], v[196:197]
	v_pk_fma_f32 v[198:199], v[4:5], v[222:223], v[198:199]
	s_mov_b64 s[6:7], 0x120000
	v_lshl_add_u64 v[252:253], v[6:7], 0, s[6:7]
	global_store_dwordx4 v[252:253], v[196:199], off
	ds_read_b128 v[220:223], v10 offset:16896
	s_waitcnt vmcnt(7) lgkmcnt(1)
	v_pk_fma_f32 v[200:201], v[2:3], v[224:225], v[200:201]
	v_pk_fma_f32 v[202:203], v[4:5], v[226:227], v[202:203]
	s_mov_b64 s[6:7], 0x130000
	v_lshl_add_u64 v[252:253], v[6:7], 0, s[6:7]
	global_store_dwordx4 v[252:253], v[200:203], off
	ds_read_b128 v[224:227], v10 offset:21120
	s_waitcnt vmcnt(7) lgkmcnt(1)
	v_pk_fma_f32 v[204:205], v[2:3], v[220:221], v[204:205]
	v_pk_fma_f32 v[206:207], v[4:5], v[222:223], v[206:207]
	s_mov_b64 s[6:7], 0x140000
	v_lshl_add_u64 v[252:253], v[6:7], 0, s[6:7]
	global_store_dwordx4 v[252:253], v[204:207], off
	ds_read_b128 v[220:223], v10 offset:25344
	s_waitcnt vmcnt(7) lgkmcnt(1)
	v_pk_fma_f32 v[208:209], v[2:3], v[224:225], v[208:209]
	v_pk_fma_f32 v[210:211], v[4:5], v[226:227], v[210:211]
	s_mov_b64 s[6:7], 0x150000
	v_lshl_add_u64 v[252:253], v[6:7], 0, s[6:7]
	global_store_dwordx4 v[252:253], v[208:211], off
	ds_read_b128 v[224:227], v10 offset:29568
	s_waitcnt vmcnt(7) lgkmcnt(1)
	v_pk_fma_f32 v[212:213], v[2:3], v[220:221], v[212:213]
	v_pk_fma_f32 v[214:215], v[4:5], v[222:223], v[214:215]
	s_mov_b64 s[6:7], 0x160000
	v_lshl_add_u64 v[252:253], v[6:7], 0, s[6:7]
	global_store_dwordx4 v[252:253], v[212:215], off
	s_waitcnt vmcnt(7) lgkmcnt(0)
; __global__ void __launch_bounds__(256, 2) fwd_megakernel(Params p) {
;     ...
;   for (int jt = (bid >> 3); jt < 8 * 16; jt += (nb >> 3)) {
;     ...
; #pragma unroll 4
;                 for (int ps = 0; ps < 16; ++ps) {
;                   const int r = ps * 8 + r0;
;                   const float4 sv = *(const float4*)(smf + r * 132 + c4 * 4);
;                   float4 xv = *(const float4*)(xin + (size_t)r * 2048 + c4 * 4);
;                   xv.x += g.x * sv.x; xv.y += g.y * sv.y; xv.z += g.z * sv.z; xv.w += g.w * sv.w;
;                   *(float4*)(ot + (size_t)r * 2048 + c4 * 4) = xv;
;                 }
;                 __syncthreads();
;               }, smem);
;   }
	v_pk_fma_f32 v[216:217], v[2:3], v[224:225], v[216:217]
	v_pk_fma_f32 v[218:219], v[4:5], v[226:227], v[218:219]
	s_mov_b64 s[6:7], 0x170000
	v_lshl_add_u64 v[252:253], v[6:7], 0, s[6:7]
	global_store_dwordx4 v[252:253], v[216:219], off
	s_mov_b64 s[6:7], 0x180000
	v_lshl_add_u64 v[252:253], v[8:9], 0, s[6:7]
	global_load_dwordx4 v[188:191], v[252:253], off
	s_mov_b64 s[6:7], 0x190000
	v_lshl_add_u64 v[252:253], v[8:9], 0, s[6:7]
	global_load_dwordx4 v[192:195], v[252:253], off
	s_mov_b64 s[6:7], 0x1a0000
	v_lshl_add_u64 v[252:253], v[8:9], 0, s[6:7]
	global_load_dwordx4 v[196:199], v[252:253], off
	s_mov_b64 s[6:7], 0x1b0000
	v_lshl_add_u64 v[252:253], v[8:9], 0, s[6:7]
	global_load_dwordx4 v[200:203], v[252:253], off
	s_mov_b64 s[6:7], 0x1c0000
	v_lshl_add_u64 v[252:253], v[8:9], 0, s[6:7]
	global_load_dwordx4 v[204:207], v[252:253], off
	s_mov_b64 s[6:7], 0x1d0000
	v_lshl_add_u64 v[252:253], v[8:9], 0, s[6:7]
	global_load_dwordx4 v[208:211], v[252:253], off
	s_mov_b64 s[6:7], 0x1e0000
	v_lshl_add_u64 v[252:253], v[8:9], 0, s[6:7]
	global_load_dwordx4 v[212:215], v[252:253], off
	s_mov_b64 s[6:7], 0x1f0000
	v_lshl_add_u64 v[252:253], v[8:9], 0, s[6:7]
	global_load_dwordx4 v[216:219], v[252:253], off
	ds_read_b128 v[220:223], v10 offset:33792
	ds_read_b128 v[224:227], v10 offset:38016
	s_waitcnt vmcnt(7) lgkmcnt(1)
	v_pk_fma_f32 v[188:189], v[2:3], v[220:221], v[188:189]
	v_pk_fma_f32 v[190:191], v[4:5], v[222:223], v[190:191]
	s_mov_b64 s[6:7], 0x180000
	v_lshl_add_u64 v[252:253], v[6:7], 0, s[6:7]
	global_store_dwordx4 v[252:253], v[188:191], off
	ds_read_b128 v[220:223], v10 offset:42240
	s_waitcnt vmcnt(7) lgkmcnt(1)
	v_pk_fma_f32 v[192:193], v[2:3], v[224:225], v[192:193]
	v_pk_fma_f32 v[194:195], v[4:5], v[226:227], v[194:195]
	s_mov_b64 s[6:7], 0x190000
	v_lshl_add_u64 v[252:253], v[6:7], 0, s[6:7]
	global_store_dwordx4 v[252:253], v[192:195], off
	ds_read_b128 v[224:227], v10 offset:46464
	s_waitcnt vmcnt(7) lgkmcnt(1)
	v_pk_fma_f32 v[196:197], v[2:3], v[220:221], v[196:197]
	v_pk_fma_f32 v[198:199], v[4:5], v[222:223], v[198:199]
	s_mov_b64 s[6:7], 0x1a0000
	v_lshl_add_u64 v[252:253], v[6:7], 0, s[6:7]
	global_store_dwordx4 v[252:253], v[196:199], off
	ds_read_b128 v[220:223], v10 offset:50688
	s_waitcnt vmcnt(7) lgkmcnt(1)
	v_pk_fma_f32 v[200:201], v[2:3], v[224:225], v[200:201]
	v_pk_fma_f32 v[202:203], v[4:5], v[226:227], v[202:203]
	s_mov_b64 s[6:7], 0x1b0000
	v_lshl_add_u64 v[252:253], v[6:7], 0, s[6:7]
	global_store_dwordx4 v[252:253], v[200:203], off
	ds_read_b128 v[224:227], v10 offset:54912
	s_waitcnt vmcnt(7) lgkmcnt(1)
	v_pk_fma_f32 v[204:205], v[2:3], v[220:221], v[204:205]
	v_pk_fma_f32 v[206:207], v[4:5], v[222:223], v[206:207]
	s_mov_b64 s[6:7], 0x1c0000
	v_lshl_add_u64 v[252:253], v[6:7], 0, s[6:7]
	global_store_dwordx4 v[252:253], v[204:207], off
	ds_read_b128 v[220:223], v10 offset:59136
	s_waitcnt vmcnt(7) lgkmcnt(1)
	v_pk_fma_f32 v[208:209], v[2:3], v[224:225], v[208:209]
	v_pk_fma_f32 v[210:211], v[4:5], v[226:227], v[210:211]
	s_mov_b64 s[6:7], 0x1d0000
	v_lshl_add_u64 v[252:253], v[6:7], 0, s[6:7]
	global_store_dwordx4 v[252:253], v[208:211], off
	ds_read_b128 v[224:227], v10 offset:63360
	s_waitcnt vmcnt(7) lgkmcnt(1)
	v_pk_fma_f32 v[212:213], v[2:3], v[220:221], v[212:213]
	v_pk_fma_f32 v[214:215], v[4:5], v[222:223], v[214:215]
	s_mov_b64 s[6:7], 0x1e0000
	v_lshl_add_u64 v[252:253], v[6:7], 0, s[6:7]
	global_store_dwordx4 v[252:253], v[212:215], off
	s_waitcnt vmcnt(7) lgkmcnt(0)
	v_pk_fma_f32 v[216:217], v[2:3], v[224:225], v[216:217]
	v_pk_fma_f32 v[218:219], v[4:5], v[226:227], v[218:219]
	s_mov_b64 s[6:7], 0x1f0000
	v_lshl_add_u64 v[252:253], v[6:7], 0, s[6:7]
	global_store_dwordx4 v[252:253], v[216:219], off
	s_lshr_b32 s6, s92, 3
	s_add_i32 s24, s24, s13
	s_add_i32 s3, s3, s6
	s_cmpk_gt_i32 s24, 0x7f
	s_barrier
	s_cbranch_scc0 .LBB0_1241
